# v15 + nontemporal loads of the residual stream in the residual epilogues
# baseline (speedup 1.0000x reference)
;     __device__ __forceinline__ unsigned u(int i) const { return (unsigned)__builtin_amdgcn_readfirstlane((int)d[i]); }
;     __device__ __forceinline__ unsigned u(int i) const { return (unsigned)__builtin_amdgcn_readfirstlane((int)d[i]); }
;     static __device__ __forceinline__ void run(const f32x4 (&acc)[2][2][4][2], const Unit& u, int wr, int wc, int fr, int fq, const float* xin, float* xout, const float* gate, float gs, const float* lazy_ssq, const float* lazy_g, ...
;         const unsigned b = (unsigned)(u.pm * BM) >> 13; const unsigned row0 = u.pm * BM + wr * 64 + fr; const unsigned col0 = u.pn * BM + wc * 32 + 8 * fq;
;         float rl[2][4], sq[2][4], sqb[2][4];
; #pragma unroll
;         for (int ai = 0; ai < 2; ++ai)
; #pragma unroll
;             for (int m = 0; m < 4; ++m) { rl[ai][m] = LAZY ? __builtin_amdgcn_rsqf(lazy_ssq[row0 + ai * HALF + m * 16] * (1.0f / 1024.0f) + 1e-6f) : 1.0f; sq[ai][m] = 0.f; sqb[ai][m] = 0.f; }
; #pragma unroll
;         for (int bj = 0; bj < 2; ++bj) {
;             const unsigned col = col0 + bj * HALF;
;             f32x4 gv[2], lg[2], wv[2], w2[2];
; #pragma unroll
;             for (int n = 0; n < 2; ++n) {
;                 gv[n] = *(const f32x4*)(gate + (b * 9216u + col + 4 * n)) * gs;
;                 lg[n] = (f32x4){1.f, 1.f, 1.f, 1.f}; if (LAZY) lg[n] = *(const f32x4*)(lazy_g + col + 4 * n);
;                 wv[n] = (f32x4){0.f, 0.f, 0.f, 0.f}; w2[n] = (f32x4){1.f, 1.f, 1.f, 1.f};
;                 if (aout) { wv[n] = *(const f32x4*)(wg + col + 4 * n) * (*(const f32x4*)(wsc + (b * 9216u + col + 4 * n)) + 1.0f); if (WG2) { w2[n] = *(const f32x4*)(wg2 + col + 4 * n); wv[n] = wv[n] * w2[n]; } }
;             }
;             f32x4 xq[2][2][2];
.LBB0_310:
	v_mov_b32_e32 v128, s85
	ds_read_b32 v129, v128
	v_mov_b32_e32 v128, v216
	s_mov_b64 s[8:9], -1
	v_readfirstlane_b32 s2, v128
	s_waitcnt lgkmcnt(0)
	v_readfirstlane_b32 s66, v129
	s_ashr_i32 s65, s2, 8
	s_bfe_u32 s64, s2, 0x20006
	v_and_b32_e32 v230, 15, v128
	v_bfe_u32 v229, v128, 4, 2
	s_mov_b64 s[26:27], 0
	s_cmp_lt_i32 s66, 2
	s_mov_b64 s[2:3], 0
	s_cbranch_scc1 .LBB0_480
	s_cmp_gt_i32 s66, 3
	s_cbranch_scc0 .LBB0_444
	s_cmp_gt_i32 s66, 4
	s_cbranch_scc0 .LBB0_375
	s_cmp_eq_u32 s66, 5
	s_mov_b64 s[2:3], -1
	s_cbranch_scc0 .LBB0_374
	v_readlane_b32 s2, v251, 31
	v_mov_b32_e32 v132, s86
	s_lshl_b32 s10, s63, 8
	v_mov_b32_e32 v128, s2
	v_readlane_b32 s2, v251, 27
	ds_read2_b64 v[134:137], v128 offset1:1
	s_lshl_b32 s11, s65, 6
	v_mov_b32_e32 v128, s2
	ds_read_b128 v[128:131], v128
	ds_read_b64 v[144:145], v132
	v_readlane_b32 s2, v251, 32
	s_add_i32 s11, s11, s10
	v_or_b32_e32 v172, s11, v230
	v_mov_b32_e32 v132, s2
	s_waitcnt lgkmcnt(0)
	v_readfirstlane_b32 s2, v128
	v_readfirstlane_b32 s3, v129
	v_mov_b32_e32 v173, v177
	v_add_u32_e32 v158, 0x80, v172
	v_lshl_add_u64 v[128:129], v[172:173], 2, s[2:3]
	v_mov_b32_e32 v159, v177
	v_add_u32_e32 v156, 0x90, v172
	v_mov_b32_e32 v157, v177
	v_add_u32_e32 v154, 0xa0, v172
	v_mov_b32_e32 v155, v177
	v_add_u32_e32 v152, 0xb0, v172
	v_mov_b32_e32 v153, v177
	v_readfirstlane_b32 s38, v136
	v_readfirstlane_b32 s39, v137
	ds_read_b32 v147, v132
	v_readfirstlane_b32 s8, v130
	v_readfirstlane_b32 s9, v131
	v_lshl_add_u64 v[130:131], v[158:159], 2, s[2:3]
	v_lshl_add_u64 v[132:133], v[156:157], 2, s[2:3]
	v_lshl_add_u64 v[136:137], v[154:155], 2, s[2:3]
	v_lshl_add_u64 v[138:139], v[152:153], 2, s[2:3]
	global_load_dword v146, v[128:129], off
	global_load_dword v196, v[128:129], off offset:64
	global_load_dword v206, v[128:129], off offset:128
	global_load_dword v210, v[128:129], off offset:192
	global_load_dword v213, v[130:131], off
	global_load_dword v212, v[132:133], off
	global_load_dword v211, v[136:137], off
	global_load_dword v197, v[138:139], off
	s_lshl_b32 s10, s64, 5
	s_lshl_b32 s2, s62, 8
	s_bfe_u32 s37, s63, 0x130005
	s_or_b32 s2, s10, s2
	v_lshl_or_b32 v184, v229, 3, s2
	s_mulk_i32 s37, 0x2400
	v_add_u32_e32 v176, s37, v184
	v_mov_b32_e32 v185, v177
	v_lshlrev_b64 v[148:149], 2, v[184:185]
	v_lshl_add_u64 v[132:133], v[176:177], 2, s[38:39]
	v_lshl_add_u64 v[180:181], s[8:9], 0, v[148:149]
	global_load_dwordx4 v[136:139], v[132:133], off nt
	global_load_dwordx4 v[128:131], v[180:181], off nt
	v_readlane_b32 s2, v251, 28
	v_readfirstlane_b32 s34, v134
	v_readfirstlane_b32 s35, v135
	v_mov_b32_e32 v134, s2
	ds_read_b128 v[140:143], v134
	v_readlane_b32 s2, v251, 29
	v_mov_b32_e32 v186, 0
	v_readfirstlane_b32 s30, v144
	v_mov_b32_e32 v134, s2
	v_readlane_b32 s2, v251, 30
	ds_read_b64 v[134:135], v134
	s_waitcnt lgkmcnt(0)
	v_readfirstlane_b32 s28, v140
	v_mov_b32_e32 v140, s2
	v_readfirstlane_b32 s29, v141
	ds_read_b64 v[140:141], v140
	s_cmp_lg_u64 s[28:29], 0
	v_readfirstlane_b32 s8, v142
	v_readfirstlane_b32 s9, v143
	v_readfirstlane_b32 s40, v134
	v_readfirstlane_b32 s41, v135
	s_cselect_b64 s[10:11], -1, 0
	v_readfirstlane_b32 s31, v145
	v_readfirstlane_b32 s36, v147
	s_waitcnt lgkmcnt(0)
	v_readfirstlane_b32 s2, v140
	v_readfirstlane_b32 s3, v141
	v_lshl_add_u64 v[182:183], s[8:9], 0, v[148:149]
	s_and_b64 vcc, exec, s[10:11]
	v_lshl_add_u64 v[144:145], v[176:177], 2, s[40:41]
	v_mov_b32_e32 v187, v186
	v_mov_b32_e32 v188, v186
	v_mov_b32_e32 v189, v186
	s_cbranch_vccz .LBB0_316
	global_load_dwordx4 v[140:143], v[144:145], off nt
	global_load_dwordx4 v[148:151], v[182:183], off nt
	s_waitcnt vmcnt(0)
	v_pk_add_f32 v[134:135], v[142:143], 1.0 op_sel_hi:[1,0]
	v_pk_add_f32 v[140:141], v[140:141], 1.0 op_sel_hi:[1,0]
	v_pk_mul_f32 v[188:189], v[150:151], v[134:135]
	v_pk_mul_f32 v[186:187], v[148:149], v[140:141]
.LBB0_316:
	global_load_dwordx4 v[140:143], v[132:133], off offset:16 nt
	s_nop 0
	global_load_dwordx4 v[132:135], v[180:181], off offset:16 nt
	v_cndmask_b32_e64 v147, 0, 1, s[10:11]
	v_cmp_ne_u32_e64 s[8:9], 1, v147
	s_andn2_b64 vcc, exec, s[10:11]
	s_cbranch_vccnz .LBB0_318
	global_load_dwordx4 v[148:151], v[144:145], off offset:16 nt
	global_load_dwordx4 v[190:193], v[182:183], off offset:16 nt
	s_waitcnt vmcnt(0)
	v_pk_add_f32 v[144:145], v[150:151], 1.0 op_sel_hi:[1,0]
	v_pk_add_f32 v[148:149], v[148:149], 1.0 op_sel_hi:[1,0]
	v_pk_mul_f32 v[194:195], v[192:193], v[144:145]
	v_pk_mul_f32 v[192:193], v[190:191], v[148:149]
	s_branch .LBB0_319

; __device__ __forceinline__ unsigned cvt_pk_bf16(float lo, float hi) { unsigned r; asm volatile("v_cvt_pk_bf16_f32 %0, %1, %2" : "=v"(r) : "v"(lo), "v"(hi)); return r; }
; #define RES_LD(buf, pp) do { _Pragma("unroll") for (int j = 0; j < 2; ++j) { const int i_ = 2 * (pp) + j; const unsigned off_ = (row0 + (i_ >> 2) * HALF + (i_ & 3) * 16) * 1024u + col; \
;                 xq[buf][j][0] = *(const f32x4*)(xin + off_); xq[buf][j][1] = *(const f32x4*)(xin + off_ + 4); } } while (0)
;     static __device__ __forceinline__ void run(const f32x4 (&acc)[2][2][4][2], const Unit& u, int wr, int wc, int fr, int fq, const float* xin, float* xout, const float* gate, float gs, const float* lazy_ssq, const float* lazy_g, ...
;     ...
;             constexpr bool DEEP = !LAZY && !WG2;
;             if (DEEP) RES_LD(0, 0);
; #pragma unroll
;             for (int pp = 0; pp < 4; ++pp) {
;                 if (DEEP) { if (pp < 3) RES_LD((pp + 1) & 1, pp + 1); } else RES_LD(pp & 1, pp);
; #pragma unroll
;                 for (int j = 0; j < 2; ++j) { const int i_ = 2 * pp + j, ai = i_ >> 2, m = i_ & 3; const unsigned off = (row0 + ai * HALF + m * 16) * 1024u + col;
;                     const f32x4 xi0 = xq[pp & 1][j][0], xi1 = xq[pp & 1][j][1];
;                     f32x4 xo0 = gv[0] * acc[ai][bj][m][0], xo1 = gv[1] * acc[ai][bj][m][1];
;                     if (LAZY) { xo0 = xo0 + xi0 * lg[0] * rl[ai][m]; xo1 = xo1 + xi1 * lg[1] * rl[ai][m]; } else { xo0 = xo0 + xi0; xo1 = xo1 + xi1; }
;                     *(f32x4*)(xout + off) = xo0; *(f32x4*)(xout + off + 4) = xo1;
;                     if (aout) { const f32x4 a0 = xo0 * wv[0], a1 = xo1 * wv[1]; u32x4 w; w.x = cvt_pk_bf16(a0[0], a0[1]); w.y = cvt_pk_bf16(a0[2], a0[3]); w.z = cvt_pk_bf16(a1[0], a1[1]); w.w = cvt_pk_bf16(a1[2], a1[3]);
;                         *(u32x4*)(aout + off) = w;
;                         sq[ai][m] += ((xo0[0] * xo0[0] + xo0[1] * xo0[1]) + (xo0[2] * xo0[2] + xo0[3] * xo0[3])) + ((xo1[0] * xo1[0] + xo1[1] * xo1[1]) + (xo1[2] * xo1[2] + xo1[3] * xo1[3]));
.LBB0_319:
	v_lshlrev_b32_e32 v175, 10, v172
	v_add_u32_e32 v176, v184, v175
	v_lshlrev_b64 v[208:209], 2, v[176:177]
	s_waitcnt vmcnt(0)
	v_pk_mul_f32 v[204:205], s[36:37], v[136:137] op_sel_hi:[0,1]
	v_lshl_add_u64 v[136:137], s[34:35], 0, v[208:209]
	v_pk_mul_f32 v[200:201], s[36:37], v[140:141] op_sel_hi:[0,1]
	v_fmamk_f32 v140, v146, 0x3a800000, v222
	global_load_dwordx4 v[148:151], v[136:137], off offset:16 nt
	global_load_dwordx4 v[144:147], v[136:137], off nt
	v_add_u32_e32 v190, 0x4000, v176
	v_mov_b32_e32 v191, v177
	v_rsq_f32_e32 v174, v140
	v_lshl_add_u64 v[140:141], v[190:191], 2, s[34:35]
	v_pk_mul_f32 v[198:199], s[36:37], v[142:143] op_sel_hi:[0,1]
	v_pk_mul_f32 v[202:203], s[36:37], v[138:139] op_sel_hi:[0,1]
	global_load_dwordx4 v[136:139], v[140:141], off offset:16 nt
	s_nop 0
	global_load_dwordx4 v[140:143], v[140:141], off nt
	v_lshl_add_u64 v[208:209], s[30:31], 0, v[208:209]
	v_mov_b32_e32 v231, 0
	s_and_b64 vcc, exec, s[8:9]
	v_mov_b32_e32 v232, 0
	s_waitcnt vmcnt(3)
	v_pk_mul_f32 v[150:151], v[134:135], v[150:151]
	s_waitcnt vmcnt(2)
	v_pk_mul_f32 v[146:147], v[130:131], v[146:147]
	v_pk_mul_f32 v[144:145], v[128:129], v[144:145]
	v_pk_mul_f32 v[148:149], v[132:133], v[148:149]
	v_pk_mul_f32 v[146:147], v[174:175], v[146:147] op_sel_hi:[0,1]
	v_pk_mul_f32 v[144:145], v[174:175], v[144:145] op_sel_hi:[0,1]
	v_pk_mul_f32 v[150:151], v[174:175], v[150:151] op_sel_hi:[0,1]
	v_pk_mul_f32 v[148:149], v[174:175], v[148:149] op_sel_hi:[0,1]
	v_pk_fma_f32 v[144:145], v[124:125], v[204:205], v[144:145]
	v_pk_fma_f32 v[146:147], v[126:127], v[202:203], v[146:147]
	v_pk_fma_f32 v[148:149], v[120:121], v[200:201], v[148:149]
	v_pk_fma_f32 v[150:151], v[122:123], v[198:199], v[150:151]
	global_store_dwordx4 v[208:209], v[144:147], off
	global_store_dwordx4 v[208:209], v[148:151], off offset:16
	s_cbranch_vccnz .LBB0_321
	v_pk_mul_f32 v[208:209], v[188:189], v[146:147]
	v_pk_mul_f32 v[214:215], v[186:187], v[144:145]
	v_pk_mul_f32 v[234:235], v[192:193], v[148:149]
	v_cvt_pk_bf16_f32 v232, v214, v215
	v_cvt_pk_bf16_f32 v233, v208, v209
	v_lshl_add_u64 v[208:209], v[176:177], 1, s[28:29]
	v_pk_mul_f32 v[236:237], v[194:195], v[150:151]
	v_cvt_pk_bf16_f32 v234, v234, v235
	s_nop 0
	v_cvt_pk_bf16_f32 v235, v236, v237
	global_store_dwordx4 v[208:209], v[232:235], off
	v_mov_b32_e32 v209, v148
	v_mov_b32_e32 v148, v145
	v_mov_b32_e32 v208, v144
	v_pk_mul_f32 v[144:145], v[148:149], v[148:149]
	v_mov_b32_e32 v149, v150
	v_mov_b32_e32 v150, v147
	v_mov_b32_e32 v148, v146
	v_pk_mul_f32 v[146:147], v[150:151], v[150:151]
	v_pk_fma_f32 v[144:145], v[208:209], v[208:209], v[144:145]
	v_pk_fma_f32 v[146:147], v[148:149], v[148:149], v[146:147]
	s_nop 0
	v_pk_add_f32 v[144:145], v[144:145], v[146:147]
	s_nop 0
	v_add_f32_e32 v232, v144, v145

; __device__ __forceinline__ unsigned cvt_pk_bf16(float lo, float hi) { unsigned r; asm volatile("v_cvt_pk_bf16_f32 %0, %1, %2" : "=v"(r) : "v"(lo), "v"(hi)); return r; }
; #define RES_LD(buf, pp) do { _Pragma("unroll") for (int j = 0; j < 2; ++j) { const int i_ = 2 * (pp) + j; const unsigned off_ = (row0 + (i_ >> 2) * HALF + (i_ & 3) * 16) * 1024u + col; \
;                 xq[buf][j][0] = *(const f32x4*)(xin + off_); xq[buf][j][1] = *(const f32x4*)(xin + off_ + 4); } } while (0)
;     static __device__ __forceinline__ void run(const f32x4 (&acc)[2][2][4][2], const Unit& u, int wr, int wc, int fr, int fq, const float* xin, float* xout, const float* gate, float gs, const float* lazy_ssq, const float* lazy_g, ...
;     ...
;             constexpr bool DEEP = !LAZY && !WG2;
;             if (DEEP) RES_LD(0, 0);
; #pragma unroll
;             for (int pp = 0; pp < 4; ++pp) {
;                 if (DEEP) { if (pp < 3) RES_LD((pp + 1) & 1, pp + 1); } else RES_LD(pp & 1, pp);
; #pragma unroll
;                 for (int j = 0; j < 2; ++j) { const int i_ = 2 * pp + j, ai = i_ >> 2, m = i_ & 3; const unsigned off = (row0 + ai * HALF + m * 16) * 1024u + col;
;                     const f32x4 xi0 = xq[pp & 1][j][0], xi1 = xq[pp & 1][j][1];
;                     f32x4 xo0 = gv[0] * acc[ai][bj][m][0], xo1 = gv[1] * acc[ai][bj][m][1];
;                     if (LAZY) { xo0 = xo0 + xi0 * lg[0] * rl[ai][m]; xo1 = xo1 + xi1 * lg[1] * rl[ai][m]; } else { xo0 = xo0 + xi0; xo1 = xo1 + xi1; }
;                     *(f32x4*)(xout + off) = xo0; *(f32x4*)(xout + off + 4) = xo1;
;                     if (aout) { const f32x4 a0 = xo0 * wv[0], a1 = xo1 * wv[1]; u32x4 w; w.x = cvt_pk_bf16(a0[0], a0[1]); w.y = cvt_pk_bf16(a0[2], a0[3]); w.z = cvt_pk_bf16(a1[0], a1[1]); w.w = cvt_pk_bf16(a1[2], a1[3]);
;                         *(u32x4*)(aout + off) = w;
;                         sq[ai][m] += ((xo0[0] * xo0[0] + xo0[1] * xo0[1]) + (xo0[2] * xo0[2] + xo0[3] * xo0[3])) + ((xo1[0] * xo1[0] + xo1[1] * xo1[1]) + (xo1[2] * xo1[2] + xo1[3] * xo1[3]));
.LBB0_323:
	v_add_u32_e32 v208, 0x8000, v176
	v_mov_b32_e32 v209, v177
	v_fmamk_f32 v136, v206, 0x3a800000, v222
	v_lshlrev_b64 v[214:215], 2, v[208:209]
	v_rsq_f32_e32 v190, v136
	v_lshl_add_u64 v[136:137], s[34:35], 0, v[214:215]
	global_load_dwordx4 v[148:151], v[136:137], off offset:16 nt
	global_load_dwordx4 v[144:147], v[136:137], off nt
	v_add_u32_e32 v206, 0xc000, v176
	v_mov_b32_e32 v207, v177
	v_lshl_add_u64 v[140:141], v[206:207], 2, s[34:35]
	global_load_dwordx4 v[136:139], v[140:141], off offset:16 nt
	s_nop 0
	global_load_dwordx4 v[140:143], v[140:141], off nt
	v_lshl_add_u64 v[214:215], s[30:31], 0, v[214:215]
	v_mov_b32_e32 v233, 0
	s_and_b64 vcc, exec, s[8:9]
	v_mov_b32_e32 v234, 0
	s_waitcnt vmcnt(3)
	v_pk_mul_f32 v[150:151], v[134:135], v[150:151]
	s_waitcnt vmcnt(2)
	v_pk_mul_f32 v[146:147], v[130:131], v[146:147]
	v_pk_mul_f32 v[144:145], v[128:129], v[144:145]
	v_pk_mul_f32 v[148:149], v[132:133], v[148:149]
	v_pk_mul_f32 v[146:147], v[190:191], v[146:147] op_sel_hi:[0,1]
	v_pk_mul_f32 v[144:145], v[190:191], v[144:145] op_sel_hi:[0,1]
	v_pk_mul_f32 v[150:151], v[190:191], v[150:151] op_sel_hi:[0,1]
	v_pk_mul_f32 v[148:149], v[190:191], v[148:149] op_sel_hi:[0,1]
	v_pk_fma_f32 v[146:147], v[94:95], v[202:203], v[146:147]
	v_pk_fma_f32 v[144:145], v[92:93], v[204:205], v[144:145]
	v_pk_fma_f32 v[150:151], v[90:91], v[198:199], v[150:151]
	v_pk_fma_f32 v[148:149], v[88:89], v[200:201], v[148:149]
	global_store_dwordx4 v[214:215], v[144:147], off
	global_store_dwordx4 v[214:215], v[148:151], off offset:16
	s_cbranch_vccnz .LBB0_325
	v_pk_mul_f32 v[234:235], v[186:187], v[144:145]
	v_pk_mul_f32 v[236:237], v[192:193], v[148:149]
	v_lshl_add_u64 v[208:209], v[208:209], 1, s[28:29]
	v_pk_mul_f32 v[214:215], v[188:189], v[146:147]
	v_pk_mul_f32 v[238:239], v[194:195], v[150:151]
	v_cvt_pk_bf16_f32 v234, v234, v235
	v_cvt_pk_bf16_f32 v235, v214, v215
	v_cvt_pk_bf16_f32 v236, v236, v237
	s_nop 0
	v_cvt_pk_bf16_f32 v237, v238, v239
	global_store_dwordx4 v[208:209], v[234:237], off
	v_mov_b32_e32 v209, v148
	v_mov_b32_e32 v148, v145
	v_mov_b32_e32 v208, v144
	v_pk_mul_f32 v[144:145], v[148:149], v[148:149]
	v_mov_b32_e32 v149, v150
	v_mov_b32_e32 v150, v147
	v_mov_b32_e32 v148, v146
	v_pk_mul_f32 v[146:147], v[150:151], v[150:151]
	v_pk_fma_f32 v[144:145], v[208:209], v[208:209], v[144:145]
	v_pk_fma_f32 v[146:147], v[148:149], v[148:149], v[146:147]
	s_nop 0
	v_pk_add_f32 v[144:145], v[144:145], v[146:147]
	s_nop 0
	v_add_f32_e32 v234, v144, v145

; __device__ __forceinline__ unsigned cvt_pk_bf16(float lo, float hi) { unsigned r; asm volatile("v_cvt_pk_bf16_f32 %0, %1, %2" : "=v"(r) : "v"(lo), "v"(hi)); return r; }
; #define RES_LD(buf, pp) do { _Pragma("unroll") for (int j = 0; j < 2; ++j) { const int i_ = 2 * (pp) + j; const unsigned off_ = (row0 + (i_ >> 2) * HALF + (i_ & 3) * 16) * 1024u + col; \
;                 xq[buf][j][0] = *(const f32x4*)(xin + off_); xq[buf][j][1] = *(const f32x4*)(xin + off_ + 4); } } while (0)
;     static __device__ __forceinline__ void run(const f32x4 (&acc)[2][2][4][2], const Unit& u, int wr, int wc, int fr, int fq, const float* xin, float* xout, const float* gate, float gs, const float* lazy_ssq, const float* lazy_g, ...
;     ...
;             constexpr bool DEEP = !LAZY && !WG2;
;             if (DEEP) RES_LD(0, 0);
; #pragma unroll
;             for (int pp = 0; pp < 4; ++pp) {
;                 if (DEEP) { if (pp < 3) RES_LD((pp + 1) & 1, pp + 1); } else RES_LD(pp & 1, pp);
; #pragma unroll
;                 for (int j = 0; j < 2; ++j) { const int i_ = 2 * pp + j, ai = i_ >> 2, m = i_ & 3; const unsigned off = (row0 + ai * HALF + m * 16) * 1024u + col;
;                     const f32x4 xi0 = xq[pp & 1][j][0], xi1 = xq[pp & 1][j][1];
;                     f32x4 xo0 = gv[0] * acc[ai][bj][m][0], xo1 = gv[1] * acc[ai][bj][m][1];
;                     if (LAZY) { xo0 = xo0 + xi0 * lg[0] * rl[ai][m]; xo1 = xo1 + xi1 * lg[1] * rl[ai][m]; } else { xo0 = xo0 + xi0; xo1 = xo1 + xi1; }
;                     *(f32x4*)(xout + off) = xo0; *(f32x4*)(xout + off + 4) = xo1;
;                     if (aout) { const f32x4 a0 = xo0 * wv[0], a1 = xo1 * wv[1]; u32x4 w; w.x = cvt_pk_bf16(a0[0], a0[1]); w.y = cvt_pk_bf16(a0[2], a0[3]); w.z = cvt_pk_bf16(a1[0], a1[1]); w.w = cvt_pk_bf16(a1[2], a1[3]);
;                         *(u32x4*)(aout + off) = w;
;                         sq[ai][m] += ((xo0[0] * xo0[0] + xo0[1] * xo0[1]) + (xo0[2] * xo0[2] + xo0[3] * xo0[3])) + ((xo1[0] * xo1[0] + xo1[1] * xo1[1]) + (xo1[2] * xo1[2] + xo1[3] * xo1[3]));
.LBB0_327:
	s_nop 0
	v_fmamk_f32 v136, v213, 0x3a800000, v222
	v_lshlrev_b32_e32 v213, 10, v158
	v_add_u32_e32 v214, v213, v184
	v_mov_b32_e32 v215, v177
	v_rsq_f32_e32 v206, v136
	v_lshl_add_u64 v[136:137], v[214:215], 2, s[34:35]
	global_load_dwordx4 v[148:151], v[136:137], off offset:16 nt
	global_load_dwordx4 v[144:147], v[136:137], off nt
	v_add_u32_e32 v136, 0x4000, v214
	v_mov_b32_e32 v137, v177
	v_lshl_add_u64 v[140:141], v[136:137], 2, s[34:35]
	global_load_dwordx4 v[136:139], v[140:141], off offset:16 nt
	s_nop 0
	global_load_dwordx4 v[140:143], v[140:141], off nt
	v_add_u32_e32 v208, 0x20000, v176
	v_mov_b32_e32 v209, v177
	v_lshl_add_u64 v[236:237], v[208:209], 2, s[30:31]
	v_mov_b32_e32 v235, 0
	s_and_b64 vcc, exec, s[8:9]
	s_waitcnt vmcnt(3)
	v_pk_mul_f32 v[150:151], v[134:135], v[150:151]
	s_waitcnt vmcnt(2)
	v_pk_mul_f32 v[146:147], v[130:131], v[146:147]
	v_pk_mul_f32 v[144:145], v[128:129], v[144:145]
	v_pk_mul_f32 v[146:147], v[206:207], v[146:147] op_sel_hi:[0,1]
	v_pk_mul_f32 v[144:145], v[206:207], v[144:145] op_sel_hi:[0,1]
	v_pk_mul_f32 v[148:149], v[132:133], v[148:149]
	v_pk_fma_f32 v[146:147], v[62:63], v[202:203], v[146:147]
	v_pk_fma_f32 v[144:145], v[60:61], v[204:205], v[144:145]
	v_pk_mul_f32 v[150:151], v[206:207], v[150:151] op_sel_hi:[0,1]
	v_pk_mul_f32 v[148:149], v[206:207], v[148:149] op_sel_hi:[0,1]
	v_pk_fma_f32 v[150:151], v[58:59], v[198:199], v[150:151]
	v_pk_fma_f32 v[148:149], v[56:57], v[200:201], v[148:149]
	global_store_dwordx4 v[236:237], v[144:147], off
	global_store_dwordx4 v[236:237], v[148:151], off offset:16
	v_mov_b32_e32 v236, 0
	s_cbranch_vccnz .LBB0_329
	v_pk_mul_f32 v[238:239], v[188:189], v[146:147]
	v_pk_mul_f32 v[236:237], v[186:187], v[144:145]
	v_lshl_add_u64 v[208:209], v[208:209], 1, s[28:29]
	v_pk_mul_f32 v[240:241], v[194:195], v[150:151]
	v_pk_mul_f32 v[242:243], v[192:193], v[148:149]
	v_cvt_pk_bf16_f32 v236, v236, v237
	v_cvt_pk_bf16_f32 v237, v238, v239
	s_nop 0
	v_cvt_pk_bf16_f32 v238, v242, v243
	v_cvt_pk_bf16_f32 v239, v240, v241
	global_store_dwordx4 v[208:209], v[236:239], off
	v_mov_b32_e32 v209, v148
	v_mov_b32_e32 v148, v145
	v_mov_b32_e32 v208, v144
	v_pk_mul_f32 v[144:145], v[148:149], v[148:149]
	v_mov_b32_e32 v149, v150
	v_mov_b32_e32 v150, v147
	v_mov_b32_e32 v148, v146
	v_pk_mul_f32 v[146:147], v[150:151], v[150:151]
	v_pk_fma_f32 v[144:145], v[208:209], v[208:209], v[144:145]
	v_pk_fma_f32 v[146:147], v[148:149], v[148:149], v[146:147]
	s_nop 0
	v_pk_add_f32 v[144:145], v[144:145], v[146:147]
	s_nop 0
	v_add_f32_e32 v236, v144, v145

; __device__ __forceinline__ unsigned cvt_pk_bf16(float lo, float hi) { unsigned r; asm volatile("v_cvt_pk_bf16_f32 %0, %1, %2" : "=v"(r) : "v"(lo), "v"(hi)); return r; }
; #define RES_LD(buf, pp) do { _Pragma("unroll") for (int j = 0; j < 2; ++j) { const int i_ = 2 * (pp) + j; const unsigned off_ = (row0 + (i_ >> 2) * HALF + (i_ & 3) * 16) * 1024u + col; \
;                 xq[buf][j][0] = *(const f32x4*)(xin + off_); xq[buf][j][1] = *(const f32x4*)(xin + off_ + 4); } } while (0)
;     static __device__ __forceinline__ void run(const f32x4 (&acc)[2][2][4][2], const Unit& u, int wr, int wc, int fr, int fq, const float* xin, float* xout, const float* gate, float gs, const float* lazy_ssq, const float* lazy_g, ...
;     ...
;             constexpr bool DEEP = !LAZY && !WG2;
;             if (DEEP) RES_LD(0, 0);
; #pragma unroll
;             for (int pp = 0; pp < 4; ++pp) {
;                 if (DEEP) { if (pp < 3) RES_LD((pp + 1) & 1, pp + 1); } else RES_LD(pp & 1, pp);
; #pragma unroll
;                 for (int j = 0; j < 2; ++j) { const int i_ = 2 * pp + j, ai = i_ >> 2, m = i_ & 3; const unsigned off = (row0 + ai * HALF + m * 16) * 1024u + col;
;                     const f32x4 xi0 = xq[pp & 1][j][0], xi1 = xq[pp & 1][j][1];
;                     f32x4 xo0 = gv[0] * acc[ai][bj][m][0], xo1 = gv[1] * acc[ai][bj][m][1];
;                     if (LAZY) { xo0 = xo0 + xi0 * lg[0] * rl[ai][m]; xo1 = xo1 + xi1 * lg[1] * rl[ai][m]; } else { xo0 = xo0 + xi0; xo1 = xo1 + xi1; }
;                     *(f32x4*)(xout + off) = xo0; *(f32x4*)(xout + off + 4) = xo1;
;                     if (aout) { const f32x4 a0 = xo0 * wv[0], a1 = xo1 * wv[1]; u32x4 w; w.x = cvt_pk_bf16(a0[0], a0[1]); w.y = cvt_pk_bf16(a0[2], a0[3]); w.z = cvt_pk_bf16(a1[0], a1[1]); w.w = cvt_pk_bf16(a1[2], a1[3]);
;                         *(u32x4*)(aout + off) = w;
;                         sq[ai][m] += ((xo0[0] * xo0[0] + xo0[1] * xo0[1]) + (xo0[2] * xo0[2] + xo0[3] * xo0[3])) + ((xo1[0] * xo1[0] + xo1[1] * xo1[1]) + (xo1[2] * xo1[2] + xo1[3] * xo1[3]));
.LBB0_331:
	s_nop 0
	v_fmamk_f32 v136, v211, 0x3a800000, v222
	v_rsq_f32_e32 v208, v136
	v_add_u32_e32 v136, 0x8000, v214
	v_mov_b32_e32 v137, v177
	v_lshl_add_u64 v[136:137], v[136:137], 2, s[34:35]
	global_load_dwordx4 v[148:151], v[136:137], off offset:16 nt
	global_load_dwordx4 v[144:147], v[136:137], off nt
	v_add_u32_e32 v136, 0xc000, v214
	v_mov_b32_e32 v137, v177
	v_lshl_add_u64 v[140:141], v[136:137], 2, s[34:35]
	global_load_dwordx4 v[136:139], v[140:141], off offset:16 nt
	s_nop 0
	global_load_dwordx4 v[140:143], v[140:141], off nt
	v_add_u32_e32 v214, 0x28000, v176
	v_mov_b32_e32 v215, v177
	v_lshl_add_u64 v[238:239], v[214:215], 2, s[30:31]
	v_mov_b32_e32 v237, 0
	s_and_b64 vcc, exec, s[8:9]
	s_waitcnt vmcnt(3)
	v_pk_mul_f32 v[150:151], v[134:135], v[150:151]
	s_waitcnt vmcnt(2)
	v_pk_mul_f32 v[146:147], v[130:131], v[146:147]
	v_pk_mul_f32 v[144:145], v[128:129], v[144:145]
	v_pk_mul_f32 v[146:147], v[208:209], v[146:147] op_sel_hi:[0,1]
	v_pk_mul_f32 v[144:145], v[208:209], v[144:145] op_sel_hi:[0,1]
	v_pk_mul_f32 v[148:149], v[132:133], v[148:149]
	v_pk_fma_f32 v[146:147], v[30:31], v[202:203], v[146:147]
	v_pk_fma_f32 v[144:145], v[28:29], v[204:205], v[144:145]
	v_pk_mul_f32 v[150:151], v[208:209], v[150:151] op_sel_hi:[0,1]
	v_pk_mul_f32 v[148:149], v[208:209], v[148:149] op_sel_hi:[0,1]
	v_pk_fma_f32 v[150:151], v[26:27], v[198:199], v[150:151]
	v_pk_fma_f32 v[148:149], v[24:25], v[200:201], v[148:149]
	global_store_dwordx4 v[238:239], v[144:147], off
	global_store_dwordx4 v[238:239], v[148:151], off offset:16
	v_mov_b32_e32 v238, 0
	s_cbranch_vccnz .LBB0_333
	v_pk_mul_f32 v[240:241], v[188:189], v[146:147]
	v_pk_mul_f32 v[238:239], v[186:187], v[144:145]
	v_lshl_add_u64 v[214:215], v[214:215], 1, s[28:29]
	v_pk_mul_f32 v[242:243], v[194:195], v[150:151]
	v_pk_mul_f32 v[244:245], v[192:193], v[148:149]
	v_cvt_pk_bf16_f32 v238, v238, v239
	v_cvt_pk_bf16_f32 v239, v240, v241
	s_nop 0
	v_cvt_pk_bf16_f32 v240, v244, v245
	v_cvt_pk_bf16_f32 v241, v242, v243
	global_store_dwordx4 v[214:215], v[238:241], off
	v_mov_b32_e32 v215, v148
	v_mov_b32_e32 v148, v145
	v_mov_b32_e32 v214, v144
	v_pk_mul_f32 v[144:145], v[148:149], v[148:149]
	v_mov_b32_e32 v149, v150
	v_mov_b32_e32 v150, v147
	v_mov_b32_e32 v148, v146
	v_pk_mul_f32 v[146:147], v[150:151], v[150:151]
	v_pk_fma_f32 v[144:145], v[214:215], v[214:215], v[144:145]
	v_pk_fma_f32 v[146:147], v[148:149], v[148:149], v[146:147]
	s_nop 0
	v_pk_add_f32 v[144:145], v[144:145], v[146:147]
	s_nop 0
	v_add_f32_e32 v238, v144, v145

;     static __device__ __forceinline__ void run(const f32x4 (&acc)[2][2][4][2], const Unit& u, int wr, int wc, int fr, int fq, const float* xin, float* xout, const float* gate, float gs, const float* lazy_ssq, const float* lazy_g, ...
;     ...
;         for (int bj = 0; bj < 2; ++bj) {
;             const unsigned col = col0 + bj * HALF;
;             f32x4 gv[2], lg[2], wv[2], w2[2];
; #pragma unroll
;             for (int n = 0; n < 2; ++n) {
;                 gv[n] = *(const f32x4*)(gate + (b * 9216u + col + 4 * n)) * gs;
;                 lg[n] = (f32x4){1.f, 1.f, 1.f, 1.f}; if (LAZY) lg[n] = *(const f32x4*)(lazy_g + col + 4 * n);
;                 wv[n] = (f32x4){0.f, 0.f, 0.f, 0.f}; w2[n] = (f32x4){1.f, 1.f, 1.f, 1.f};
;                 if (aout) { wv[n] = *(const f32x4*)(wg + col + 4 * n) * (*(const f32x4*)(wsc + (b * 9216u + col + 4 * n)) + 1.0f); if (WG2) { w2[n] = *(const f32x4*)(wg2 + col + 4 * n); wv[n] = wv[n] * w2[n]; } }
;             }
;             f32x4 xq[2][2][2];
;     ...
;             constexpr bool DEEP = !LAZY && !WG2;
;             if (DEEP) RES_LD(0, 0);
; #pragma unroll
;             for (int pp = 0; pp < 4; ++pp) {
;                 if (DEEP) { if (pp < 3) RES_LD((pp + 1) & 1, pp + 1); } else RES_LD(pp & 1, pp);
; #pragma unroll
;                 for (int j = 0; j < 2; ++j) { const int i_ = 2 * pp + j, ai = i_ >> 2, m = i_ & 3; const unsigned off = (row0 + ai * HALF + m * 16) * 1024u + col;
;                     const f32x4 xi0 = xq[pp & 1][j][0], xi1 = xq[pp & 1][j][1];
;                     f32x4 xo0 = gv[0] * acc[ai][bj][m][0], xo1 = gv[1] * acc[ai][bj][m][1];
;                     if (LAZY) { xo0 = xo0 + xi0 * lg[0] * rl[ai][m]; xo1 = xo1 + xi1 * lg[1] * rl[ai][m]; } else { xo0 = xo0 + xi0; xo1 = xo1 + xi1; }
;                     *(f32x4*)(xout + off) = xo0; *(f32x4*)(xout + off + 4) = xo1;
;                     if (aout) { const f32x4 a0 = xo0 * wv[0], a1 = xo1 * wv[1]; u32x4 w; w.x = cvt_pk_bf16(a0[0], a0[1]); w.y = cvt_pk_bf16(a0[2], a0[3]); w.z = cvt_pk_bf16(a1[0], a1[1]); w.w = cvt_pk_bf16(a1[2], a1[3]);
;                         *(u32x4*)(aout + off) = w;
;                         sq[ai][m] += ((xo0[0] * xo0[0] + xo0[1] * xo0[1]) + (xo0[2] * xo0[2] + xo0[3] * xo0[3])) + ((xo1[0] * xo1[0] + xo1[1] * xo1[1]) + (xo1[2] * xo1[2] + xo1[3] * xo1[3]));
.LBB0_335:
	v_or_b32_e32 v202, 0x80, v184
	v_add_u32_e32 v176, s37, v202
	v_lshl_add_u64 v[132:133], v[176:177], 2, s[38:39]
	global_load_dwordx4 v[140:143], v[132:133], off nt
	global_load_dwordx4 v[128:131], v[180:181], off offset:512 nt
	v_mov_b32_e32 v184, 0
	s_and_b64 vcc, exec, s[8:9]
	v_lshl_add_u64 v[136:137], v[176:177], 2, s[40:41]
	v_mov_b32_e32 v186, 0
	v_mov_b32_e32 v187, 0
	v_mov_b32_e32 v188, 0
	v_mov_b32_e32 v189, 0
	s_cbranch_vccnz .LBB0_337
	global_load_dwordx4 v[144:147], v[136:137], off nt
	global_load_dwordx4 v[148:151], v[182:183], off offset:512 nt
	s_waitcnt vmcnt(1)
	v_pk_add_f32 v[134:135], v[146:147], 1.0 op_sel_hi:[1,0]
	v_pk_add_f32 v[138:139], v[144:145], 1.0 op_sel_hi:[1,0]
	s_waitcnt vmcnt(0)
	v_pk_mul_f32 v[188:189], v[150:151], v[134:135]
	v_pk_mul_f32 v[186:187], v[148:149], v[138:139]
.LBB0_337:
	global_load_dwordx4 v[148:151], v[132:133], off offset:16 nt
	s_nop 0
	global_load_dwordx4 v[132:135], v[180:181], off offset:528 nt
	s_and_b64 vcc, exec, s[8:9]
	v_mov_b32_e32 v185, 0
	v_mov_b32_e32 v180, 0
	v_mov_b32_e32 v181, 0
	s_cbranch_vccnz .LBB0_339
	global_load_dwordx4 v[136:139], v[136:137], off offset:16 nt
	s_nop 0
	global_load_dwordx4 v[144:147], v[182:183], off offset:528 nt
	s_waitcnt vmcnt(1)
	v_pk_add_f32 v[138:139], v[138:139], 1.0 op_sel_hi:[1,0]
	v_pk_add_f32 v[136:137], v[136:137], 1.0 op_sel_hi:[1,0]
	s_waitcnt vmcnt(0)
	v_pk_mul_f32 v[180:181], v[146:147], v[138:139]
	v_pk_mul_f32 v[184:185], v[144:145], v[136:137]
.LBB0_339:
	v_add_u32_e32 v176, v202, v175
	v_lshlrev_b64 v[204:205], 2, v[176:177]
	v_lshl_add_u64 v[136:137], s[34:35], 0, v[204:205]
	global_load_dwordx4 v[240:243], v[136:137], off nt
	global_load_dwordx4 v[244:247], v[136:137], off offset:16 nt
	v_mov_b32_e32 v201, v177
	v_add_u32_e32 v200, 0x4000, v176
	v_lshl_add_u64 v[144:145], v[200:201], 2, s[34:35]
	global_load_dwordx4 v[136:139], v[144:145], off offset:16 nt
	s_nop 0
	global_load_dwordx4 v[144:147], v[144:145], off nt
	s_mov_b32 s37, s36
	s_mov_b32 s38, s36
	s_mov_b32 s39, s36
	v_mov_b32_e32 v175, v174
	v_mov_b32_e32 v248, v174
	v_mov_b32_e32 v249, v174
	s_waitcnt vmcnt(5)
	v_pk_mul_f32 v[182:183], s[38:39], v[150:151]
	v_pk_mul_f32 v[192:193], s[36:37], v[148:149]
	v_pk_mul_f32 v[194:195], s[38:39], v[142:143]
	v_pk_mul_f32 v[198:199], s[36:37], v[140:141]
	s_and_b64 vcc, exec, s[8:9]
	v_lshl_add_u64 v[204:205], s[30:31], 0, v[204:205]
	s_waitcnt vmcnt(3)
	v_pk_mul_f32 v[140:141], v[130:131], v[242:243]
	v_pk_mul_f32 v[142:143], v[128:129], v[240:241]
	s_waitcnt vmcnt(2)
	v_pk_mul_f32 v[148:149], v[134:135], v[246:247]
	v_pk_mul_f32 v[150:151], v[132:133], v[244:245]
	v_pk_mul_f32 v[140:141], v[248:249], v[140:141]
	v_pk_mul_f32 v[142:143], v[174:175], v[142:143]
	v_pk_mul_f32 v[240:241], v[248:249], v[148:149]
	v_pk_mul_f32 v[174:175], v[174:175], v[150:151]
	v_pk_fma_f32 v[150:151], v[118:119], v[194:195], v[140:141]
	v_pk_fma_f32 v[148:149], v[116:117], v[198:199], v[142:143]
	v_pk_fma_f32 v[142:143], v[114:115], v[182:183], v[240:241]
	v_pk_fma_f32 v[140:141], v[112:113], v[192:193], v[174:175]
	global_store_dwordx4 v[204:205], v[148:151], off
	global_store_dwordx4 v[204:205], v[140:143], off offset:16
	s_cbranch_vccnz .LBB0_341
	v_pk_mul_f32 v[174:175], v[188:189], v[150:151]
	v_pk_mul_f32 v[204:205], v[186:187], v[148:149]
	v_pk_mul_f32 v[242:243], v[184:185], v[140:141]
	v_cvt_pk_bf16_f32 v240, v204, v205
	v_cvt_pk_bf16_f32 v241, v174, v175
	v_lshl_add_u64 v[174:175], v[176:177], 1, s[28:29]
	v_pk_mul_f32 v[244:245], v[180:181], v[142:143]
	v_cvt_pk_bf16_f32 v242, v242, v243
	s_nop 0
	v_cvt_pk_bf16_f32 v243, v244, v245
	global_store_dwordx4 v[174:175], v[240:243], off
	v_mov_b32_e32 v175, v140
	v_mov_b32_e32 v140, v149
	v_mov_b32_e32 v149, v142
	v_mov_b32_e32 v142, v151
	v_mov_b32_e32 v174, v148
	v_pk_mul_f32 v[140:141], v[140:141], v[140:141]
	v_mov_b32_e32 v148, v150
	v_pk_mul_f32 v[142:143], v[142:143], v[142:143]
	v_pk_fma_f32 v[140:141], v[174:175], v[174:175], v[140:141]
	v_pk_fma_f32 v[142:143], v[148:149], v[148:149], v[142:143]
	s_nop 0
	v_pk_add_f32 v[140:141], v[140:141], v[142:143]
	s_nop 0
	v_add_f32_e32 v140, v140, v141
	v_add_f32_e32 v232, v232, v140

; __device__ __forceinline__ unsigned cvt_pk_bf16(float lo, float hi) { unsigned r; asm volatile("v_cvt_pk_bf16_f32 %0, %1, %2" : "=v"(r) : "v"(lo), "v"(hi)); return r; }
; #define RES_LD(buf, pp) do { _Pragma("unroll") for (int j = 0; j < 2; ++j) { const int i_ = 2 * (pp) + j; const unsigned off_ = (row0 + (i_ >> 2) * HALF + (i_ & 3) * 16) * 1024u + col; \
;                 xq[buf][j][0] = *(const f32x4*)(xin + off_); xq[buf][j][1] = *(const f32x4*)(xin + off_ + 4); } } while (0)
;     static __device__ __forceinline__ void run(const f32x4 (&acc)[2][2][4][2], const Unit& u, int wr, int wc, int fr, int fq, const float* xin, float* xout, const float* gate, float gs, const float* lazy_ssq, const float* lazy_g, ...
;     ...
;             constexpr bool DEEP = !LAZY && !WG2;
;             if (DEEP) RES_LD(0, 0);
; #pragma unroll
;             for (int pp = 0; pp < 4; ++pp) {
;                 if (DEEP) { if (pp < 3) RES_LD((pp + 1) & 1, pp + 1); } else RES_LD(pp & 1, pp);
; #pragma unroll
;                 for (int j = 0; j < 2; ++j) { const int i_ = 2 * pp + j, ai = i_ >> 2, m = i_ & 3; const unsigned off = (row0 + ai * HALF + m * 16) * 1024u + col;
;                     const f32x4 xi0 = xq[pp & 1][j][0], xi1 = xq[pp & 1][j][1];
;                     f32x4 xo0 = gv[0] * acc[ai][bj][m][0], xo1 = gv[1] * acc[ai][bj][m][1];
;                     if (LAZY) { xo0 = xo0 + xi0 * lg[0] * rl[ai][m]; xo1 = xo1 + xi1 * lg[1] * rl[ai][m]; } else { xo0 = xo0 + xi0; xo1 = xo1 + xi1; }
;                     *(f32x4*)(xout + off) = xo0; *(f32x4*)(xout + off + 4) = xo1;
;                     if (aout) { const f32x4 a0 = xo0 * wv[0], a1 = xo1 * wv[1]; u32x4 w; w.x = cvt_pk_bf16(a0[0], a0[1]); w.y = cvt_pk_bf16(a0[2], a0[3]); w.z = cvt_pk_bf16(a1[0], a1[1]); w.w = cvt_pk_bf16(a1[2], a1[3]);
;                         *(u32x4*)(aout + off) = w;
;                         sq[ai][m] += ((xo0[0] * xo0[0] + xo0[1] * xo0[1]) + (xo0[2] * xo0[2] + xo0[3] * xo0[3])) + ((xo1[0] * xo1[0] + xo1[1] * xo1[1]) + (xo1[2] * xo1[2] + xo1[3] * xo1[3]));
.LBB0_343:
	v_add_u32_e32 v196, 0x8000, v176
	v_mov_b32_e32 v197, v177
	v_lshlrev_b64 v[200:201], 2, v[196:197]
	v_lshl_add_u64 v[136:137], s[34:35], 0, v[200:201]
	global_load_dwordx4 v[144:147], v[136:137], off nt
	global_load_dwordx4 v[148:151], v[136:137], off offset:16 nt
	v_add_u32_e32 v174, 0xc000, v176
	v_mov_b32_e32 v175, v177
	v_lshl_add_u64 v[140:141], v[174:175], 2, s[34:35]
	global_load_dwordx4 v[136:139], v[140:141], off offset:16 nt
	s_nop 0
	global_load_dwordx4 v[140:143], v[140:141], off nt
	v_mov_b32_e32 v191, v190
	v_mov_b32_e32 v204, v190
	v_mov_b32_e32 v205, v190
	s_and_b64 vcc, exec, s[8:9]
	v_lshl_add_u64 v[200:201], s[30:31], 0, v[200:201]
	s_waitcnt vmcnt(3)
	v_pk_mul_f32 v[146:147], v[130:131], v[146:147]
	v_pk_mul_f32 v[144:145], v[128:129], v[144:145]
	s_waitcnt vmcnt(2)
	v_pk_mul_f32 v[150:151], v[134:135], v[150:151]
	v_pk_mul_f32 v[148:149], v[132:133], v[148:149]
	v_pk_mul_f32 v[146:147], v[204:205], v[146:147]
	v_pk_mul_f32 v[144:145], v[190:191], v[144:145]
	v_pk_mul_f32 v[204:205], v[204:205], v[150:151]
	v_pk_mul_f32 v[190:191], v[190:191], v[148:149]
	v_pk_fma_f32 v[150:151], v[86:87], v[194:195], v[146:147]
	v_pk_fma_f32 v[148:149], v[84:85], v[198:199], v[144:145]
	v_pk_fma_f32 v[146:147], v[82:83], v[182:183], v[204:205]
	v_pk_fma_f32 v[144:145], v[80:81], v[192:193], v[190:191]
	global_store_dwordx4 v[200:201], v[148:151], off
	global_store_dwordx4 v[200:201], v[144:147], off offset:16
	s_cbranch_vccnz .LBB0_345
	v_pk_mul_f32 v[190:191], v[188:189], v[150:151]
	v_pk_mul_f32 v[200:201], v[186:187], v[148:149]
	v_pk_mul_f32 v[242:243], v[184:185], v[144:145]
	v_cvt_pk_bf16_f32 v240, v200, v201
	v_cvt_pk_bf16_f32 v241, v190, v191
	v_lshl_add_u64 v[190:191], v[196:197], 1, s[28:29]
	v_pk_mul_f32 v[204:205], v[180:181], v[146:147]
	v_cvt_pk_bf16_f32 v242, v242, v243
	s_nop 0
	v_cvt_pk_bf16_f32 v243, v204, v205
	global_store_dwordx4 v[190:191], v[240:243], off
	v_mov_b32_e32 v191, v144
	v_mov_b32_e32 v144, v149
	v_mov_b32_e32 v149, v146
	v_mov_b32_e32 v146, v151
	v_mov_b32_e32 v190, v148
	v_pk_mul_f32 v[144:145], v[144:145], v[144:145]
	v_mov_b32_e32 v148, v150
	v_pk_mul_f32 v[146:147], v[146:147], v[146:147]
	v_pk_fma_f32 v[144:145], v[190:191], v[190:191], v[144:145]
	v_pk_fma_f32 v[146:147], v[148:149], v[148:149], v[146:147]
	s_nop 0
	v_pk_add_f32 v[144:145], v[144:145], v[146:147]
	s_nop 0
	v_add_f32_e32 v144, v144, v145
	v_add_f32_e32 v234, v234, v144

; __device__ __forceinline__ unsigned cvt_pk_bf16(float lo, float hi) { unsigned r; asm volatile("v_cvt_pk_bf16_f32 %0, %1, %2" : "=v"(r) : "v"(lo), "v"(hi)); return r; }
; #define RES_LD(buf, pp) do { _Pragma("unroll") for (int j = 0; j < 2; ++j) { const int i_ = 2 * (pp) + j; const unsigned off_ = (row0 + (i_ >> 2) * HALF + (i_ & 3) * 16) * 1024u + col; \
;                 xq[buf][j][0] = *(const f32x4*)(xin + off_); xq[buf][j][1] = *(const f32x4*)(xin + off_ + 4); } } while (0)
;     static __device__ __forceinline__ void run(const f32x4 (&acc)[2][2][4][2], const Unit& u, int wr, int wc, int fr, int fq, const float* xin, float* xout, const float* gate, float gs, const float* lazy_ssq, const float* lazy_g, ...
;     ...
;             constexpr bool DEEP = !LAZY && !WG2;
;             if (DEEP) RES_LD(0, 0);
; #pragma unroll
;             for (int pp = 0; pp < 4; ++pp) {
;                 if (DEEP) { if (pp < 3) RES_LD((pp + 1) & 1, pp + 1); } else RES_LD(pp & 1, pp);
; #pragma unroll
;                 for (int j = 0; j < 2; ++j) { const int i_ = 2 * pp + j, ai = i_ >> 2, m = i_ & 3; const unsigned off = (row0 + ai * HALF + m * 16) * 1024u + col;
;                     const f32x4 xi0 = xq[pp & 1][j][0], xi1 = xq[pp & 1][j][1];
;                     f32x4 xo0 = gv[0] * acc[ai][bj][m][0], xo1 = gv[1] * acc[ai][bj][m][1];
;                     if (LAZY) { xo0 = xo0 + xi0 * lg[0] * rl[ai][m]; xo1 = xo1 + xi1 * lg[1] * rl[ai][m]; } else { xo0 = xo0 + xi0; xo1 = xo1 + xi1; }
;                     *(f32x4*)(xout + off) = xo0; *(f32x4*)(xout + off + 4) = xo1;
;                     if (aout) { const f32x4 a0 = xo0 * wv[0], a1 = xo1 * wv[1]; u32x4 w; w.x = cvt_pk_bf16(a0[0], a0[1]); w.y = cvt_pk_bf16(a0[2], a0[3]); w.z = cvt_pk_bf16(a1[0], a1[1]); w.w = cvt_pk_bf16(a1[2], a1[3]);
;                         *(u32x4*)(aout + off) = w;
;                         sq[ai][m] += ((xo0[0] * xo0[0] + xo0[1] * xo0[1]) + (xo0[2] * xo0[2] + xo0[3] * xo0[3])) + ((xo1[0] * xo1[0] + xo1[1] * xo1[1]) + (xo1[2] * xo1[2] + xo1[3] * xo1[3]));
.LBB0_347:
	v_add_u32_e32 v174, v213, v202
	v_mov_b32_e32 v175, v177
	v_lshl_add_u64 v[136:137], v[174:175], 2, s[34:35]
	global_load_dwordx4 v[148:151], v[136:137], off offset:16 nt
	global_load_dwordx4 v[144:147], v[136:137], off nt
	v_add_u32_e32 v136, 0x4000, v174
	v_mov_b32_e32 v137, v177
	v_lshl_add_u64 v[140:141], v[136:137], 2, s[34:35]
	global_load_dwordx4 v[136:139], v[140:141], off offset:16 nt
	s_nop 0
	global_load_dwordx4 v[140:143], v[140:141], off nt
	v_mov_b32_e32 v207, v206
	v_mov_b32_e32 v196, v206
	v_mov_b32_e32 v197, v206
	v_add_u32_e32 v190, 0x20000, v176
	v_mov_b32_e32 v191, v177
	s_and_b64 vcc, exec, s[8:9]
	s_waitcnt vmcnt(3)
	v_pk_mul_f32 v[150:151], v[134:135], v[150:151]
	s_waitcnt vmcnt(2)
	v_pk_mul_f32 v[146:147], v[130:131], v[146:147]
	v_pk_mul_f32 v[144:145], v[128:129], v[144:145]
	v_pk_mul_f32 v[148:149], v[132:133], v[148:149]
	v_pk_mul_f32 v[146:147], v[196:197], v[146:147]
	v_pk_mul_f32 v[144:145], v[206:207], v[144:145]
	v_pk_mul_f32 v[150:151], v[196:197], v[150:151]
	v_pk_mul_f32 v[148:149], v[206:207], v[148:149]
	v_pk_fma_f32 v[146:147], v[54:55], v[194:195], v[146:147]
	v_pk_fma_f32 v[144:145], v[52:53], v[198:199], v[144:145]
	v_pk_fma_f32 v[150:151], v[50:51], v[182:183], v[150:151]
	v_pk_fma_f32 v[148:149], v[48:49], v[192:193], v[148:149]
	v_lshl_add_u64 v[196:197], v[190:191], 2, s[30:31]
	global_store_dwordx4 v[196:197], v[144:147], off
	global_store_dwordx4 v[196:197], v[148:151], off offset:16
	s_cbranch_vccnz .LBB0_349
	v_pk_mul_f32 v[200:201], v[186:187], v[144:145]
	v_pk_mul_f32 v[202:203], v[184:185], v[148:149]
	v_lshl_add_u64 v[190:191], v[190:191], 1, s[28:29]
	v_pk_mul_f32 v[196:197], v[188:189], v[146:147]
	v_pk_mul_f32 v[204:205], v[180:181], v[150:151]
	v_cvt_pk_bf16_f32 v200, v200, v201
	v_cvt_pk_bf16_f32 v201, v196, v197
	v_cvt_pk_bf16_f32 v202, v202, v203
	s_nop 0
	v_cvt_pk_bf16_f32 v203, v204, v205
	global_store_dwordx4 v[190:191], v[200:203], off
	v_mov_b32_e32 v191, v148
	v_mov_b32_e32 v148, v145
	v_mov_b32_e32 v190, v144
	v_pk_mul_f32 v[144:145], v[148:149], v[148:149]
	v_mov_b32_e32 v149, v150
	v_mov_b32_e32 v150, v147
	v_mov_b32_e32 v148, v146
	v_pk_mul_f32 v[146:147], v[150:151], v[150:151]
	v_pk_fma_f32 v[144:145], v[190:191], v[190:191], v[144:145]
	v_pk_fma_f32 v[146:147], v[148:149], v[148:149], v[146:147]
	s_nop 0
	v_pk_add_f32 v[144:145], v[144:145], v[146:147]
	s_nop 0
	v_add_f32_e32 v144, v144, v145
	v_add_f32_e32 v236, v236, v144

; __device__ __forceinline__ unsigned cvt_pk_bf16(float lo, float hi) { unsigned r; asm volatile("v_cvt_pk_bf16_f32 %0, %1, %2" : "=v"(r) : "v"(lo), "v"(hi)); return r; }
; #define RES_LD(buf, pp) do { _Pragma("unroll") for (int j = 0; j < 2; ++j) { const int i_ = 2 * (pp) + j; const unsigned off_ = (row0 + (i_ >> 2) * HALF + (i_ & 3) * 16) * 1024u + col; \
;                 xq[buf][j][0] = *(const f32x4*)(xin + off_); xq[buf][j][1] = *(const f32x4*)(xin + off_ + 4); } } while (0)
;     static __device__ __forceinline__ void run(const f32x4 (&acc)[2][2][4][2], const Unit& u, int wr, int wc, int fr, int fq, const float* xin, float* xout, const float* gate, float gs, const float* lazy_ssq, const float* lazy_g, ...
;     ...
;             constexpr bool DEEP = !LAZY && !WG2;
;             if (DEEP) RES_LD(0, 0);
; #pragma unroll
;             for (int pp = 0; pp < 4; ++pp) {
;                 if (DEEP) { if (pp < 3) RES_LD((pp + 1) & 1, pp + 1); } else RES_LD(pp & 1, pp);
; #pragma unroll
;                 for (int j = 0; j < 2; ++j) { const int i_ = 2 * pp + j, ai = i_ >> 2, m = i_ & 3; const unsigned off = (row0 + ai * HALF + m * 16) * 1024u + col;
;                     const f32x4 xi0 = xq[pp & 1][j][0], xi1 = xq[pp & 1][j][1];
;                     f32x4 xo0 = gv[0] * acc[ai][bj][m][0], xo1 = gv[1] * acc[ai][bj][m][1];
;                     if (LAZY) { xo0 = xo0 + xi0 * lg[0] * rl[ai][m]; xo1 = xo1 + xi1 * lg[1] * rl[ai][m]; } else { xo0 = xo0 + xi0; xo1 = xo1 + xi1; }
;                     *(f32x4*)(xout + off) = xo0; *(f32x4*)(xout + off + 4) = xo1;
;                     if (aout) { const f32x4 a0 = xo0 * wv[0], a1 = xo1 * wv[1]; u32x4 w; w.x = cvt_pk_bf16(a0[0], a0[1]); w.y = cvt_pk_bf16(a0[2], a0[3]); w.z = cvt_pk_bf16(a1[0], a1[1]); w.w = cvt_pk_bf16(a1[2], a1[3]);
;                         *(u32x4*)(aout + off) = w;
;                         sq[ai][m] += ((xo0[0] * xo0[0] + xo0[1] * xo0[1]) + (xo0[2] * xo0[2] + xo0[3] * xo0[3])) + ((xo1[0] * xo1[0] + xo1[1] * xo1[1]) + (xo1[2] * xo1[2] + xo1[3] * xo1[3]));
.LBB0_351:
	s_nop 0
	v_add_u32_e32 v136, 0x8000, v174
	v_mov_b32_e32 v137, v177
	v_lshl_add_u64 v[136:137], v[136:137], 2, s[34:35]
	global_load_dwordx4 v[148:151], v[136:137], off offset:16 nt
	global_load_dwordx4 v[144:147], v[136:137], off nt
	v_add_u32_e32 v136, 0xc000, v174
	v_mov_b32_e32 v137, v177
	v_lshl_add_u64 v[140:141], v[136:137], 2, s[34:35]
	global_load_dwordx4 v[136:139], v[140:141], off offset:16 nt
	s_nop 0
	global_load_dwordx4 v[140:143], v[140:141], off nt
	v_mov_b32_e32 v209, v208
	v_mov_b32_e32 v190, v208
	v_mov_b32_e32 v191, v208
	v_add_u32_e32 v174, 0x28000, v176
	v_mov_b32_e32 v175, v177
	s_and_b64 vcc, exec, s[8:9]
	s_waitcnt vmcnt(3)
	v_pk_mul_f32 v[150:151], v[134:135], v[150:151]
	s_waitcnt vmcnt(2)
	v_pk_mul_f32 v[146:147], v[130:131], v[146:147]
	v_pk_mul_f32 v[144:145], v[128:129], v[144:145]
	v_pk_mul_f32 v[148:149], v[132:133], v[148:149]
	v_pk_mul_f32 v[146:147], v[190:191], v[146:147]
	v_pk_mul_f32 v[144:145], v[208:209], v[144:145]
	v_pk_mul_f32 v[150:151], v[190:191], v[150:151]
	v_pk_mul_f32 v[148:149], v[208:209], v[148:149]
	v_pk_fma_f32 v[146:147], v[22:23], v[194:195], v[146:147]
	v_pk_fma_f32 v[144:145], v[20:21], v[198:199], v[144:145]
	v_pk_fma_f32 v[150:151], v[18:19], v[182:183], v[150:151]
	v_pk_fma_f32 v[148:149], v[16:17], v[192:193], v[148:149]
	v_lshl_add_u64 v[190:191], v[174:175], 2, s[30:31]
	global_store_dwordx4 v[190:191], v[144:147], off
	global_store_dwordx4 v[190:191], v[148:151], off offset:16
	s_cbranch_vccnz .LBB0_353
	v_pk_mul_f32 v[202:203], v[184:185], v[148:149]
	v_lshl_add_u64 v[174:175], v[174:175], 1, s[28:29]
	v_pk_mul_f32 v[190:191], v[188:189], v[146:147]
	v_pk_mul_f32 v[196:197], v[186:187], v[144:145]
	v_pk_mul_f32 v[204:205], v[180:181], v[150:151]
	v_cvt_pk_bf16_f32 v200, v196, v197
	v_cvt_pk_bf16_f32 v201, v190, v191
	v_cvt_pk_bf16_f32 v202, v202, v203
	s_nop 0
	v_cvt_pk_bf16_f32 v203, v204, v205
	global_store_dwordx4 v[174:175], v[200:203], off
	v_mov_b32_e32 v175, v148
	v_mov_b32_e32 v148, v145
	v_mov_b32_e32 v174, v144
	v_pk_mul_f32 v[144:145], v[148:149], v[148:149]
	v_mov_b32_e32 v149, v150
	v_mov_b32_e32 v150, v147
	v_mov_b32_e32 v148, v146
	v_pk_mul_f32 v[146:147], v[150:151], v[150:151]
	v_pk_fma_f32 v[144:145], v[174:175], v[174:175], v[144:145]
	v_pk_fma_f32 v[146:147], v[148:149], v[148:149], v[146:147]
	s_nop 0
	v_pk_add_f32 v[144:145], v[144:145], v[146:147]
	s_nop 0
	v_add_f32_e32 v144, v144, v145
	v_add_f32_e32 v238, v238, v144

;     __device__ __forceinline__ unsigned u(int i) const { return (unsigned)__builtin_amdgcn_readfirstlane((int)d[i]); }
;     __device__ __forceinline__ unsigned u(int i) const { return (unsigned)__builtin_amdgcn_readfirstlane((int)d[i]); }
;     static __device__ __forceinline__ void run(const f32x4 (&acc)[2][2][4][2], const Unit& u, int wr, int wc, int fr, int fq, const float* xin, float* xout, const float* gate, float gs, const float* lazy_ssq, const float* lazy_g, ...
;         const unsigned b = (unsigned)(u.pm * BM) >> 13; const unsigned row0 = u.pm * BM + wr * 64 + fr; const unsigned col0 = u.pn * BM + wc * 32 + 8 * fq;
;         float rl[2][4], sq[2][4], sqb[2][4];
; #pragma unroll
;         for (int ai = 0; ai < 2; ++ai)
; #pragma unroll
;             for (int m = 0; m < 4; ++m) { rl[ai][m] = LAZY ? __builtin_amdgcn_rsqf(lazy_ssq[row0 + ai * HALF + m * 16] * (1.0f / 1024.0f) + 1e-6f) : 1.0f; sq[ai][m] = 0.f; sqb[ai][m] = 0.f; }
; #pragma unroll
;         for (int bj = 0; bj < 2; ++bj) {
;             const unsigned col = col0 + bj * HALF;
;             f32x4 gv[2], lg[2], wv[2], w2[2];
; #pragma unroll
;             for (int n = 0; n < 2; ++n) {
;                 gv[n] = *(const f32x4*)(gate + (b * 9216u + col + 4 * n)) * gs;
;                 lg[n] = (f32x4){1.f, 1.f, 1.f, 1.f}; if (LAZY) lg[n] = *(const f32x4*)(lazy_g + col + 4 * n);
;                 wv[n] = (f32x4){0.f, 0.f, 0.f, 0.f}; w2[n] = (f32x4){1.f, 1.f, 1.f, 1.f};
;                 if (aout) { wv[n] = *(const f32x4*)(wg + col + 4 * n) * (*(const f32x4*)(wsc + (b * 9216u + col + 4 * n)) + 1.0f); if (WG2) { w2[n] = *(const f32x4*)(wg2 + col + 4 * n); wv[n] = wv[n] * w2[n]; } }
.LBB0_375:
	s_and_b64 vcc, exec, s[8:9]
	s_cbranch_vccz .LBB0_443
	v_readlane_b32 s8, v251, 31
	s_lshl_b32 s9, s62, 8
	s_bfe_u32 s41, s63, 0x130005
	v_mov_b32_e32 v128, s8
	ds_read2_b64 v[128:131], v128 offset1:1
	s_lshl_b32 s8, s64, 5
	s_or_b32 s8, s8, s9
	v_mov_b32_e32 v132, s86
	v_lshl_or_b32 v192, v229, 3, s8
	s_mulk_i32 s41, 0x2400
	ds_read_b64 v[140:141], v132
	s_waitcnt lgkmcnt(0)
	v_readfirstlane_b32 s42, v130
	v_readfirstlane_b32 s43, v131
	v_add_u32_e32 v176, s41, v192
	v_readlane_b32 s8, v251, 32
	v_lshl_add_u64 v[130:131], v[176:177], 2, s[42:43]
	global_load_dwordx4 v[136:139], v[130:131], off nt
	v_readfirstlane_b32 s38, v128
	v_mov_b32_e32 v128, s8
	v_readlane_b32 s8, v251, 28
	v_readfirstlane_b32 s36, v140
	v_readfirstlane_b32 s37, v141
	v_mov_b32_e32 v132, s8
	ds_read_b32 v128, v128
	ds_read_b128 v[132:135], v132
	v_readlane_b32 s8, v251, 29
	v_readlane_b32 s10, v251, 30
	v_mov_b32_e32 v193, v177
	s_waitcnt lgkmcnt(0)
	v_readfirstlane_b32 s40, v128
	v_mov_b32_e32 v128, s8
	ds_read_b128 v[140:143], v128
	v_mov_b32_e32 v128, s10
	v_readfirstlane_b32 s34, v132
	v_readfirstlane_b32 s35, v133
	v_readfirstlane_b32 s8, v134
	v_readfirstlane_b32 s9, v135
	ds_read_b128 v[132:135], v128
	v_readfirstlane_b32 s39, v129
	s_waitcnt lgkmcnt(0)
	v_readfirstlane_b32 s68, v142
	v_readfirstlane_b32 s69, v143
	s_cmp_lg_u64 s[34:35], 0
	v_lshlrev_b64 v[128:129], 2, v[192:193]
	v_readfirstlane_b32 s44, v140
	v_readfirstlane_b32 s45, v141
	s_cselect_b64 s[30:31], -1, 0
	v_lshl_add_u64 v[190:191], s[8:9], 0, v[128:129]
	v_lshl_add_u64 v[188:189], s[68:69], 0, v[128:129]
	v_mov_b32_e32 v186, 0
	v_mov_b32_e32 v128, 1.0
	v_readfirstlane_b32 s10, v132
	v_readfirstlane_b32 s11, v133
	v_readfirstlane_b32 s28, v134
	v_readfirstlane_b32 s29, v135
	s_and_b64 vcc, exec, s[30:31]
	v_lshl_add_u64 v[140:141], v[176:177], 2, s[44:45]
	v_mov_b32_e32 v132, 1.0
	v_mov_b32_e32 v133, v128
	v_mov_b32_e32 v134, 1.0
	v_mov_b32_e32 v135, 1.0
	v_mov_b32_e32 v187, v186
	v_mov_b32_e32 v194, v186
	v_mov_b32_e32 v195, v186
	s_cbranch_vccz .LBB0_378
	global_load_dwordx4 v[132:135], v[190:191], off nt
	global_load_dwordx4 v[142:145], v[140:141], off nt
	s_waitcnt vmcnt(0)
	v_pk_add_f32 v[144:145], v[144:145], 1.0 op_sel_hi:[1,0]
	v_pk_add_f32 v[142:143], v[142:143], 1.0 op_sel_hi:[1,0]
	v_pk_mul_f32 v[144:145], v[134:135], v[144:145]
	v_pk_mul_f32 v[142:143], v[132:133], v[142:143]
	global_load_dwordx4 v[132:135], v[188:189], off nt
	s_waitcnt vmcnt(0)
	v_pk_mul_f32 v[194:195], v[134:135], v[144:145]
	v_pk_mul_f32 v[186:187], v[132:133], v[142:143]
.LBB0_378:
	global_load_dwordx4 v[144:147], v[130:131], off offset:16 nt
	v_cndmask_b32_e64 v129, 0, 1, s[30:31]
	v_cmp_ne_u32_e64 s[8:9], 1, v129
	s_andn2_b64 vcc, exec, s[30:31]
	s_cbranch_vccnz .LBB0_380
	global_load_dwordx4 v[128:131], v[190:191], off offset:16 nt
	s_nop 0
	global_load_dwordx4 v[140:143], v[140:141], off offset:16 nt
	s_waitcnt vmcnt(0)
	v_pk_add_f32 v[142:143], v[142:143], 1.0 op_sel_hi:[1,0]
	v_pk_add_f32 v[140:141], v[140:141], 1.0 op_sel_hi:[1,0]
	v_pk_mul_f32 v[142:143], v[130:131], v[142:143]
	v_pk_mul_f32 v[140:141], v[128:129], v[140:141]
	global_load_dwordx4 v[128:131], v[188:189], off offset:16 nt
	s_waitcnt vmcnt(0)
	v_pk_mul_f32 v[198:199], v[130:131], v[142:143]
	v_pk_mul_f32 v[196:197], v[128:129], v[140:141]
	s_branch .LBB0_381

; __device__ __forceinline__ unsigned cvt_pk_bf16(float lo, float hi) { unsigned r; asm volatile("v_cvt_pk_bf16_f32 %0, %1, %2" : "=v"(r) : "v"(lo), "v"(hi)); return r; }
; #define RES_LD(buf, pp) do { _Pragma("unroll") for (int j = 0; j < 2; ++j) { const int i_ = 2 * (pp) + j; const unsigned off_ = (row0 + (i_ >> 2) * HALF + (i_ & 3) * 16) * 1024u + col; \
;                 xq[buf][j][0] = *(const f32x4*)(xin + off_); xq[buf][j][1] = *(const f32x4*)(xin + off_ + 4); } } while (0)
;     static __device__ __forceinline__ void run(const f32x4 (&acc)[2][2][4][2], const Unit& u, int wr, int wc, int fr, int fq, const float* xin, float* xout, const float* gate, float gs, const float* lazy_ssq, const float* lazy_g, ...
;     ...
;             constexpr bool DEEP = !LAZY && !WG2;
;             if (DEEP) RES_LD(0, 0);
; #pragma unroll
;             for (int pp = 0; pp < 4; ++pp) {
;                 if (DEEP) { if (pp < 3) RES_LD((pp + 1) & 1, pp + 1); } else RES_LD(pp & 1, pp);
; #pragma unroll
;                 for (int j = 0; j < 2; ++j) { const int i_ = 2 * pp + j, ai = i_ >> 2, m = i_ & 3; const unsigned off = (row0 + ai * HALF + m * 16) * 1024u + col;
;                     const f32x4 xi0 = xq[pp & 1][j][0], xi1 = xq[pp & 1][j][1];
;                     f32x4 xo0 = gv[0] * acc[ai][bj][m][0], xo1 = gv[1] * acc[ai][bj][m][1];
;                     if (LAZY) { xo0 = xo0 + xi0 * lg[0] * rl[ai][m]; xo1 = xo1 + xi1 * lg[1] * rl[ai][m]; } else { xo0 = xo0 + xi0; xo1 = xo1 + xi1; }
;                     *(f32x4*)(xout + off) = xo0; *(f32x4*)(xout + off + 4) = xo1;
;                     if (aout) { const f32x4 a0 = xo0 * wv[0], a1 = xo1 * wv[1]; u32x4 w; w.x = cvt_pk_bf16(a0[0], a0[1]); w.y = cvt_pk_bf16(a0[2], a0[3]); w.z = cvt_pk_bf16(a1[0], a1[1]); w.w = cvt_pk_bf16(a1[2], a1[3]);
;                         *(u32x4*)(aout + off) = w;
;                         sq[ai][m] += ((xo0[0] * xo0[0] + xo0[1] * xo0[1]) + (xo0[2] * xo0[2] + xo0[3] * xo0[3])) + ((xo1[0] * xo1[0] + xo1[1] * xo1[1]) + (xo1[2] * xo1[2] + xo1[3] * xo1[3]));
;                         if (WG2) { const f32x4 b0 = xo0 * w2[0], b1 = xo1 * w2[1]; sqb[ai][m] += ((b0[0] * b0[0] + b0[1] * b0[1]) + (b0[2] * b0[2] + b0[3] * b0[3])) + ((b1[0] * b1[0] + b1[1] * b1[1]) + (b1[2] * b1[2] + b1[3] * b1[3])); } } }
.LBB0_381:
	s_lshl_b32 s67, s63, 8
	s_lshl_b32 s68, s65, 6
	s_add_i32 s68, s68, s67
	v_or_b32_e32 v152, s68, v230
	v_lshlrev_b32_e32 v153, 10, v152
	v_add_u32_e32 v176, v192, v153
	v_lshlrev_b64 v[154:155], 2, v[176:177]
	v_lshl_add_u64 v[140:141], s[38:39], 0, v[154:155]
	v_add_u32_e32 v156, 0x4000, v176
	v_mov_b32_e32 v157, v177
	global_load_dwordx4 v[172:175], v[140:141], off nt
	global_load_dwordx4 v[180:183], v[140:141], off offset:16 nt
	v_lshl_add_u64 v[148:149], v[156:157], 2, s[38:39]
	global_load_dwordx4 v[140:143], v[148:149], off offset:16 nt
	s_nop 0
	global_load_dwordx4 v[148:151], v[148:149], off nt
	s_waitcnt vmcnt(0)
	v_pk_mul_f32 v[202:203], s[40:41], v[146:147] op_sel_hi:[0,1]
	v_pk_mul_f32 v[200:201], s[40:41], v[144:145] op_sel_hi:[0,1]
	v_pk_mul_f32 v[204:205], s[40:41], v[138:139] op_sel_hi:[0,1]
	v_pk_mul_f32 v[206:207], s[40:41], v[136:137] op_sel_hi:[0,1]
	s_and_b64 vcc, exec, s[8:9]
	v_lshl_add_u64 v[154:155], s[36:37], 0, v[154:155]
	v_pk_fma_f32 v[146:147], v[126:127], v[204:205], v[174:175]
	v_pk_fma_f32 v[144:145], v[124:125], v[206:207], v[172:173]
	v_pk_fma_f32 v[138:139], v[122:123], v[202:203], v[182:183]
	v_pk_fma_f32 v[136:137], v[120:121], v[200:201], v[180:181]
	global_store_dwordx4 v[154:155], v[144:147], off
	global_store_dwordx4 v[154:155], v[136:139], off offset:16
	s_cbranch_vccnz .LBB0_383
	v_pk_mul_f32 v[154:155], v[194:195], v[146:147]
	v_pk_mul_f32 v[158:159], v[186:187], v[144:145]
	v_pk_mul_f32 v[180:181], v[198:199], v[138:139]
	v_pk_mul_f32 v[174:175], v[196:197], v[136:137]
	v_cvt_pk_bf16_f32 v172, v158, v159
	v_cvt_pk_bf16_f32 v173, v154, v155
	v_lshl_add_u64 v[154:155], v[176:177], 1, s[34:35]
	v_pk_mul_f32 v[158:159], v[132:133], v[144:145]
	v_cvt_pk_bf16_f32 v174, v174, v175
	v_cvt_pk_bf16_f32 v175, v180, v181
	global_store_dwordx4 v[154:155], v[172:175], off
	v_pk_mul_f32 v[154:155], v[134:135], v[146:147]
	v_mov_b32_e32 v181, v158
	v_mov_b32_e32 v158, v145
	v_mov_b32_e32 v180, v144
	v_pk_mul_f32 v[144:145], v[158:159], v[158:159]
	v_mov_b32_e32 v159, v154
	v_mov_b32_e32 v154, v147
	v_mov_b32_e32 v158, v146
	v_pk_mul_f32 v[146:147], v[154:155], v[154:155]
	v_pk_mul_f32 v[174:175], v[128:129], v[136:137]
	v_pk_fma_f32 v[144:145], v[180:181], v[180:181], v[144:145]
	v_pk_fma_f32 v[146:147], v[158:159], v[158:159], v[146:147]
	v_pk_mul_f32 v[172:173], v[130:131], v[138:139]
	v_pk_add_f32 v[144:145], v[144:145], v[146:147]
	v_mov_b32_e32 v147, v174
	v_mov_b32_e32 v174, v137
	v_mov_b32_e32 v146, v136
	v_pk_mul_f32 v[136:137], v[174:175], v[174:175]
	s_nop 0
	v_pk_fma_f32 v[136:137], v[146:147], v[146:147], v[136:137]
	v_mov_b32_e32 v147, v172
	v_mov_b32_e32 v172, v139
	v_mov_b32_e32 v146, v138
	v_pk_mul_f32 v[138:139], v[172:173], v[172:173]
	s_nop 0
	v_pk_fma_f32 v[138:139], v[146:147], v[146:147], v[138:139]
	s_nop 0
	v_pk_add_f32 v[136:137], v[136:137], v[138:139]
	s_nop 0
	v_pk_add_f32 v[154:155], v[144:145], v[136:137]
	s_branch .LBB0_384

; __device__ __forceinline__ unsigned cvt_pk_bf16(float lo, float hi) { unsigned r; asm volatile("v_cvt_pk_bf16_f32 %0, %1, %2" : "=v"(r) : "v"(lo), "v"(hi)); return r; }
; #define RES_LD(buf, pp) do { _Pragma("unroll") for (int j = 0; j < 2; ++j) { const int i_ = 2 * (pp) + j; const unsigned off_ = (row0 + (i_ >> 2) * HALF + (i_ & 3) * 16) * 1024u + col; \
;                 xq[buf][j][0] = *(const f32x4*)(xin + off_); xq[buf][j][1] = *(const f32x4*)(xin + off_ + 4); } } while (0)
;     static __device__ __forceinline__ void run(const f32x4 (&acc)[2][2][4][2], const Unit& u, int wr, int wc, int fr, int fq, const float* xin, float* xout, const float* gate, float gs, const float* lazy_ssq, const float* lazy_g, ...
;     ...
;             constexpr bool DEEP = !LAZY && !WG2;
;             if (DEEP) RES_LD(0, 0);
; #pragma unroll
;             for (int pp = 0; pp < 4; ++pp) {
;                 if (DEEP) { if (pp < 3) RES_LD((pp + 1) & 1, pp + 1); } else RES_LD(pp & 1, pp);
; #pragma unroll
;                 for (int j = 0; j < 2; ++j) { const int i_ = 2 * pp + j, ai = i_ >> 2, m = i_ & 3; const unsigned off = (row0 + ai * HALF + m * 16) * 1024u + col;
;                     const f32x4 xi0 = xq[pp & 1][j][0], xi1 = xq[pp & 1][j][1];
;                     f32x4 xo0 = gv[0] * acc[ai][bj][m][0], xo1 = gv[1] * acc[ai][bj][m][1];
;                     if (LAZY) { xo0 = xo0 + xi0 * lg[0] * rl[ai][m]; xo1 = xo1 + xi1 * lg[1] * rl[ai][m]; } else { xo0 = xo0 + xi0; xo1 = xo1 + xi1; }
;                     *(f32x4*)(xout + off) = xo0; *(f32x4*)(xout + off + 4) = xo1;
;                     if (aout) { const f32x4 a0 = xo0 * wv[0], a1 = xo1 * wv[1]; u32x4 w; w.x = cvt_pk_bf16(a0[0], a0[1]); w.y = cvt_pk_bf16(a0[2], a0[3]); w.z = cvt_pk_bf16(a1[0], a1[1]); w.w = cvt_pk_bf16(a1[2], a1[3]);
;                         *(u32x4*)(aout + off) = w;
;                         sq[ai][m] += ((xo0[0] * xo0[0] + xo0[1] * xo0[1]) + (xo0[2] * xo0[2] + xo0[3] * xo0[3])) + ((xo1[0] * xo1[0] + xo1[1] * xo1[1]) + (xo1[2] * xo1[2] + xo1[3] * xo1[3]));
;                         if (WG2) { const f32x4 b0 = xo0 * w2[0], b1 = xo1 * w2[1]; sqb[ai][m] += ((b0[0] * b0[0] + b0[1] * b0[1]) + (b0[2] * b0[2] + b0[3] * b0[3])) + ((b1[0] * b1[0] + b1[1] * b1[1]) + (b1[2] * b1[2] + b1[3] * b1[3])); } } }
.LBB0_387:
	v_add_u32_e32 v158, 0x8000, v176
	v_mov_b32_e32 v159, v177
	v_lshlrev_b64 v[148:149], 2, v[158:159]
	v_lshl_add_u64 v[136:137], s[38:39], 0, v[148:149]
	v_add_u32_e32 v172, 0xc000, v176
	v_mov_b32_e32 v173, v177
	global_load_dwordx4 v[144:147], v[136:137], off nt
	global_load_dwordx4 v[180:183], v[136:137], off offset:16 nt
	v_lshl_add_u64 v[140:141], v[172:173], 2, s[38:39]
	global_load_dwordx4 v[136:139], v[140:141], off offset:16 nt
	s_nop 0
	global_load_dwordx4 v[140:143], v[140:141], off nt
	s_and_b64 vcc, exec, s[8:9]
	v_lshl_add_u64 v[174:175], s[36:37], 0, v[148:149]
	s_waitcnt vmcnt(3)
	v_pk_fma_f32 v[150:151], v[94:95], v[204:205], v[146:147]
	v_pk_fma_f32 v[148:149], v[92:93], v[206:207], v[144:145]
	s_waitcnt vmcnt(2)
	v_pk_fma_f32 v[146:147], v[90:91], v[202:203], v[182:183]
	v_pk_fma_f32 v[144:145], v[88:89], v[200:201], v[180:181]
	global_store_dwordx4 v[174:175], v[148:151], off
	global_store_dwordx4 v[174:175], v[144:147], off offset:16
	s_cbranch_vccnz .LBB0_389
	v_pk_mul_f32 v[174:175], v[194:195], v[150:151]
	v_pk_mul_f32 v[180:181], v[186:187], v[148:149]
	v_pk_mul_f32 v[184:185], v[198:199], v[146:147]
	v_pk_mul_f32 v[182:183], v[196:197], v[144:145]
	v_cvt_pk_bf16_f32 v180, v180, v181
	v_cvt_pk_bf16_f32 v181, v174, v175
	v_lshl_add_u64 v[158:159], v[158:159], 1, s[34:35]
	v_pk_mul_f32 v[174:175], v[132:133], v[148:149]
	v_cvt_pk_bf16_f32 v182, v182, v183
	v_cvt_pk_bf16_f32 v183, v184, v185
	global_store_dwordx4 v[158:159], v[180:183], off
	v_pk_mul_f32 v[158:159], v[134:135], v[150:151]
	v_mov_b32_e32 v185, v174
	v_mov_b32_e32 v174, v149
	v_mov_b32_e32 v184, v148
	v_pk_mul_f32 v[148:149], v[174:175], v[174:175]
	v_mov_b32_e32 v175, v158
	v_mov_b32_e32 v158, v151
	v_mov_b32_e32 v174, v150
	v_pk_mul_f32 v[150:151], v[158:159], v[158:159]
	v_pk_mul_f32 v[182:183], v[128:129], v[144:145]
	v_pk_fma_f32 v[148:149], v[184:185], v[184:185], v[148:149]
	v_pk_fma_f32 v[150:151], v[174:175], v[174:175], v[150:151]
	v_pk_mul_f32 v[180:181], v[130:131], v[146:147]
	v_pk_add_f32 v[148:149], v[148:149], v[150:151]
	v_mov_b32_e32 v151, v182
	v_mov_b32_e32 v182, v145
	v_mov_b32_e32 v150, v144
	v_pk_mul_f32 v[144:145], v[182:183], v[182:183]
	s_nop 0
	v_pk_fma_f32 v[144:145], v[150:151], v[150:151], v[144:145]
	v_mov_b32_e32 v151, v180
	v_mov_b32_e32 v180, v147
	v_mov_b32_e32 v150, v146
	v_pk_mul_f32 v[146:147], v[180:181], v[180:181]
	s_nop 0
	v_pk_fma_f32 v[146:147], v[150:151], v[150:151], v[146:147]
	s_nop 0
	v_pk_add_f32 v[144:145], v[144:145], v[146:147]
	s_nop 0
	v_pk_add_f32 v[158:159], v[148:149], v[144:145]
	s_branch .LBB0_390

; __device__ __forceinline__ unsigned cvt_pk_bf16(float lo, float hi) { unsigned r; asm volatile("v_cvt_pk_bf16_f32 %0, %1, %2" : "=v"(r) : "v"(lo), "v"(hi)); return r; }
; #define RES_LD(buf, pp) do { _Pragma("unroll") for (int j = 0; j < 2; ++j) { const int i_ = 2 * (pp) + j; const unsigned off_ = (row0 + (i_ >> 2) * HALF + (i_ & 3) * 16) * 1024u + col; \
;                 xq[buf][j][0] = *(const f32x4*)(xin + off_); xq[buf][j][1] = *(const f32x4*)(xin + off_ + 4); } } while (0)
;     static __device__ __forceinline__ void run(const f32x4 (&acc)[2][2][4][2], const Unit& u, int wr, int wc, int fr, int fq, const float* xin, float* xout, const float* gate, float gs, const float* lazy_ssq, const float* lazy_g, ...
;     ...
;             constexpr bool DEEP = !LAZY && !WG2;
;             if (DEEP) RES_LD(0, 0);
; #pragma unroll
;             for (int pp = 0; pp < 4; ++pp) {
;                 if (DEEP) { if (pp < 3) RES_LD((pp + 1) & 1, pp + 1); } else RES_LD(pp & 1, pp);
; #pragma unroll
;                 for (int j = 0; j < 2; ++j) { const int i_ = 2 * pp + j, ai = i_ >> 2, m = i_ & 3; const unsigned off = (row0 + ai * HALF + m * 16) * 1024u + col;
;                     const f32x4 xi0 = xq[pp & 1][j][0], xi1 = xq[pp & 1][j][1];
;                     f32x4 xo0 = gv[0] * acc[ai][bj][m][0], xo1 = gv[1] * acc[ai][bj][m][1];
;                     if (LAZY) { xo0 = xo0 + xi0 * lg[0] * rl[ai][m]; xo1 = xo1 + xi1 * lg[1] * rl[ai][m]; } else { xo0 = xo0 + xi0; xo1 = xo1 + xi1; }
;                     *(f32x4*)(xout + off) = xo0; *(f32x4*)(xout + off + 4) = xo1;
;                     if (aout) { const f32x4 a0 = xo0 * wv[0], a1 = xo1 * wv[1]; u32x4 w; w.x = cvt_pk_bf16(a0[0], a0[1]); w.y = cvt_pk_bf16(a0[2], a0[3]); w.z = cvt_pk_bf16(a1[0], a1[1]); w.w = cvt_pk_bf16(a1[2], a1[3]);
;                         *(u32x4*)(aout + off) = w;
;                         sq[ai][m] += ((xo0[0] * xo0[0] + xo0[1] * xo0[1]) + (xo0[2] * xo0[2] + xo0[3] * xo0[3])) + ((xo1[0] * xo1[0] + xo1[1] * xo1[1]) + (xo1[2] * xo1[2] + xo1[3] * xo1[3]));
;                         if (WG2) { const f32x4 b0 = xo0 * w2[0], b1 = xo1 * w2[1]; sqb[ai][m] += ((b0[0] * b0[0] + b0[1] * b0[1]) + (b0[2] * b0[2] + b0[3] * b0[3])) + ((b1[0] * b1[0] + b1[1] * b1[1]) + (b1[2] * b1[2] + b1[3] * b1[3])); } } }
.LBB0_393:
	v_add_u32_e32 v172, 0x80, v152
	v_lshlrev_b32_e32 v173, 10, v172
	v_add_u32_e32 v184, v173, v192
	v_mov_b32_e32 v185, v177
	v_lshl_add_u64 v[136:137], v[184:185], 2, s[38:39]
	global_load_dwordx4 v[144:147], v[136:137], off offset:16 nt
	global_load_dwordx4 v[148:151], v[136:137], off nt
	v_add_u32_e32 v136, 0x4000, v184
	v_mov_b32_e32 v137, v177
	v_lshl_add_u64 v[140:141], v[136:137], 2, s[38:39]
	global_load_dwordx4 v[136:139], v[140:141], off offset:16 nt
	s_nop 0
	global_load_dwordx4 v[140:143], v[140:141], off nt
	v_add_u32_e32 v180, 0x20000, v176
	v_mov_b32_e32 v181, v177
	v_lshl_add_u64 v[182:183], v[180:181], 2, s[36:37]
	s_and_b64 vcc, exec, s[8:9]
	s_waitcnt vmcnt(3)
	v_pk_fma_f32 v[146:147], v[58:59], v[202:203], v[146:147]
	s_waitcnt vmcnt(2)
	v_pk_fma_f32 v[150:151], v[62:63], v[204:205], v[150:151]
	v_pk_fma_f32 v[148:149], v[60:61], v[206:207], v[148:149]
	v_pk_fma_f32 v[144:145], v[56:57], v[200:201], v[144:145]
	global_store_dwordx4 v[182:183], v[148:151], off
	global_store_dwordx4 v[182:183], v[144:147], off offset:16
	s_cbranch_vccnz .LBB0_395
	v_pk_mul_f32 v[182:183], v[194:195], v[150:151]
	v_pk_mul_f32 v[208:209], v[186:187], v[148:149]
	v_pk_mul_f32 v[212:213], v[198:199], v[146:147]
	v_pk_mul_f32 v[210:211], v[196:197], v[144:145]
	v_cvt_pk_bf16_f32 v208, v208, v209
	v_cvt_pk_bf16_f32 v209, v182, v183
	v_lshl_add_u64 v[180:181], v[180:181], 1, s[34:35]
	v_pk_mul_f32 v[182:183], v[132:133], v[148:149]
	v_cvt_pk_bf16_f32 v210, v210, v211
	v_cvt_pk_bf16_f32 v211, v212, v213
	global_store_dwordx4 v[180:181], v[208:211], off
	v_pk_mul_f32 v[180:181], v[134:135], v[150:151]
	v_mov_b32_e32 v213, v182
	v_mov_b32_e32 v182, v149
	v_mov_b32_e32 v212, v148
	v_pk_mul_f32 v[148:149], v[182:183], v[182:183]
	v_mov_b32_e32 v183, v180
	v_mov_b32_e32 v180, v151
	v_mov_b32_e32 v182, v150
	v_pk_mul_f32 v[150:151], v[180:181], v[180:181]
	v_pk_mul_f32 v[210:211], v[128:129], v[144:145]
	v_pk_fma_f32 v[148:149], v[212:213], v[212:213], v[148:149]
	v_pk_fma_f32 v[150:151], v[182:183], v[182:183], v[150:151]
	v_pk_mul_f32 v[208:209], v[130:131], v[146:147]
	v_pk_add_f32 v[148:149], v[148:149], v[150:151]
	v_mov_b32_e32 v151, v210
	v_mov_b32_e32 v210, v145
	v_mov_b32_e32 v150, v144
	v_pk_mul_f32 v[144:145], v[210:211], v[210:211]
	s_nop 0
	v_pk_fma_f32 v[144:145], v[150:151], v[150:151], v[144:145]
	v_mov_b32_e32 v151, v208
	v_mov_b32_e32 v208, v147
	v_mov_b32_e32 v150, v146
	v_pk_mul_f32 v[146:147], v[208:209], v[208:209]
	s_nop 0
	v_pk_fma_f32 v[146:147], v[150:151], v[150:151], v[146:147]
	s_nop 0
	v_pk_add_f32 v[144:145], v[144:145], v[146:147]
	s_nop 0
	v_pk_add_f32 v[180:181], v[148:149], v[144:145]
	s_branch .LBB0_396

; __device__ __forceinline__ unsigned cvt_pk_bf16(float lo, float hi) { unsigned r; asm volatile("v_cvt_pk_bf16_f32 %0, %1, %2" : "=v"(r) : "v"(lo), "v"(hi)); return r; }
; #define RES_LD(buf, pp) do { _Pragma("unroll") for (int j = 0; j < 2; ++j) { const int i_ = 2 * (pp) + j; const unsigned off_ = (row0 + (i_ >> 2) * HALF + (i_ & 3) * 16) * 1024u + col; \
;                 xq[buf][j][0] = *(const f32x4*)(xin + off_); xq[buf][j][1] = *(const f32x4*)(xin + off_ + 4); } } while (0)
;     static __device__ __forceinline__ void run(const f32x4 (&acc)[2][2][4][2], const Unit& u, int wr, int wc, int fr, int fq, const float* xin, float* xout, const float* gate, float gs, const float* lazy_ssq, const float* lazy_g, ...
;     ...
;             constexpr bool DEEP = !LAZY && !WG2;
;             if (DEEP) RES_LD(0, 0);
; #pragma unroll
;             for (int pp = 0; pp < 4; ++pp) {
;                 if (DEEP) { if (pp < 3) RES_LD((pp + 1) & 1, pp + 1); } else RES_LD(pp & 1, pp);
; #pragma unroll
;                 for (int j = 0; j < 2; ++j) { const int i_ = 2 * pp + j, ai = i_ >> 2, m = i_ & 3; const unsigned off = (row0 + ai * HALF + m * 16) * 1024u + col;
;                     const f32x4 xi0 = xq[pp & 1][j][0], xi1 = xq[pp & 1][j][1];
;                     f32x4 xo0 = gv[0] * acc[ai][bj][m][0], xo1 = gv[1] * acc[ai][bj][m][1];
;                     if (LAZY) { xo0 = xo0 + xi0 * lg[0] * rl[ai][m]; xo1 = xo1 + xi1 * lg[1] * rl[ai][m]; } else { xo0 = xo0 + xi0; xo1 = xo1 + xi1; }
;                     *(f32x4*)(xout + off) = xo0; *(f32x4*)(xout + off + 4) = xo1;
;                     if (aout) { const f32x4 a0 = xo0 * wv[0], a1 = xo1 * wv[1]; u32x4 w; w.x = cvt_pk_bf16(a0[0], a0[1]); w.y = cvt_pk_bf16(a0[2], a0[3]); w.z = cvt_pk_bf16(a1[0], a1[1]); w.w = cvt_pk_bf16(a1[2], a1[3]);
;                         *(u32x4*)(aout + off) = w;
;                         sq[ai][m] += ((xo0[0] * xo0[0] + xo0[1] * xo0[1]) + (xo0[2] * xo0[2] + xo0[3] * xo0[3])) + ((xo1[0] * xo1[0] + xo1[1] * xo1[1]) + (xo1[2] * xo1[2] + xo1[3] * xo1[3]));
;                         if (WG2) { const f32x4 b0 = xo0 * w2[0], b1 = xo1 * w2[1]; sqb[ai][m] += ((b0[0] * b0[0] + b0[1] * b0[1]) + (b0[2] * b0[2] + b0[3] * b0[3])) + ((b1[0] * b1[0] + b1[1] * b1[1]) + (b1[2] * b1[2] + b1[3] * b1[3])); } } }
.LBB0_399:
	v_add_u32_e32 v136, 0x8000, v184
	v_mov_b32_e32 v137, v177
	v_lshl_add_u64 v[136:137], v[136:137], 2, s[38:39]
	global_load_dwordx4 v[144:147], v[136:137], off offset:16 nt
	global_load_dwordx4 v[148:151], v[136:137], off nt
	v_add_u32_e32 v136, 0xc000, v184
	v_mov_b32_e32 v137, v177
	v_lshl_add_u64 v[140:141], v[136:137], 2, s[38:39]
	global_load_dwordx4 v[136:139], v[140:141], off offset:16 nt
	s_nop 0
	global_load_dwordx4 v[140:143], v[140:141], off nt
	v_add_u32_e32 v184, 0x28000, v176
	v_mov_b32_e32 v185, v177
	v_lshl_add_u64 v[208:209], v[184:185], 2, s[36:37]
	s_and_b64 vcc, exec, s[8:9]
	s_waitcnt vmcnt(3)
	v_pk_fma_f32 v[146:147], v[26:27], v[202:203], v[146:147]
	s_waitcnt vmcnt(2)
	v_pk_fma_f32 v[150:151], v[30:31], v[204:205], v[150:151]
	v_pk_fma_f32 v[148:149], v[28:29], v[206:207], v[148:149]
	v_pk_fma_f32 v[144:145], v[24:25], v[200:201], v[144:145]
	global_store_dwordx4 v[208:209], v[148:151], off
	global_store_dwordx4 v[208:209], v[144:147], off offset:16
	s_cbranch_vccnz .LBB0_401
	v_pk_mul_f32 v[208:209], v[186:187], v[148:149]
	v_pk_mul_f32 v[210:211], v[194:195], v[150:151]
	v_cvt_pk_bf16_f32 v208, v208, v209
	v_lshl_add_u64 v[184:185], v[184:185], 1, s[34:35]
	v_cvt_pk_bf16_f32 v209, v210, v211
	v_pk_mul_f32 v[212:213], v[198:199], v[146:147]
	v_pk_mul_f32 v[214:215], v[196:197], v[144:145]
	s_nop 0
	v_cvt_pk_bf16_f32 v210, v214, v215
	v_cvt_pk_bf16_f32 v211, v212, v213
	global_store_dwordx4 v[184:185], v[208:211], off
	v_pk_mul_f32 v[184:185], v[134:135], v[150:151]
	v_mov_b32_e32 v214, v148
	v_pk_mul_f32 v[208:209], v[132:133], v[148:149]
	v_pk_mul_f32 v[212:213], v[128:129], v[144:145]
	v_mov_b32_e32 v215, v208
	v_mov_b32_e32 v208, v149
	v_pk_mul_f32 v[148:149], v[208:209], v[208:209]
	v_mov_b32_e32 v209, v184
	v_mov_b32_e32 v184, v151
	v_mov_b32_e32 v208, v150
	v_pk_mul_f32 v[150:151], v[184:185], v[184:185]
	v_pk_fma_f32 v[148:149], v[214:215], v[214:215], v[148:149]
	v_pk_fma_f32 v[150:151], v[208:209], v[208:209], v[150:151]
	v_pk_mul_f32 v[210:211], v[130:131], v[146:147]
	v_pk_add_f32 v[148:149], v[148:149], v[150:151]
	v_mov_b32_e32 v151, v212
	v_mov_b32_e32 v212, v145
	v_mov_b32_e32 v150, v144
	v_pk_mul_f32 v[144:145], v[212:213], v[212:213]
	s_nop 0
	v_pk_fma_f32 v[144:145], v[150:151], v[150:151], v[144:145]
	v_mov_b32_e32 v151, v210
	v_mov_b32_e32 v210, v147
	v_mov_b32_e32 v150, v146
	v_pk_mul_f32 v[146:147], v[210:211], v[210:211]
	s_nop 0
	v_pk_fma_f32 v[146:147], v[150:151], v[150:151], v[146:147]
	s_nop 0
	v_pk_add_f32 v[144:145], v[144:145], v[146:147]
	s_nop 0
	v_pk_add_f32 v[184:185], v[148:149], v[144:145]
	s_branch .LBB0_402

;     static __device__ __forceinline__ void run(const f32x4 (&acc)[2][2][4][2], const Unit& u, int wr, int wc, int fr, int fq, const float* xin, float* xout, const float* gate, float gs, const float* lazy_ssq, const float* lazy_g, ...
;     ...
;         for (int bj = 0; bj < 2; ++bj) {
;             const unsigned col = col0 + bj * HALF;
;             f32x4 gv[2], lg[2], wv[2], w2[2];
; #pragma unroll
;             for (int n = 0; n < 2; ++n) {
;                 gv[n] = *(const f32x4*)(gate + (b * 9216u + col + 4 * n)) * gs;
;                 lg[n] = (f32x4){1.f, 1.f, 1.f, 1.f}; if (LAZY) lg[n] = *(const f32x4*)(lazy_g + col + 4 * n);
;                 wv[n] = (f32x4){0.f, 0.f, 0.f, 0.f}; w2[n] = (f32x4){1.f, 1.f, 1.f, 1.f};
;                 if (aout) { wv[n] = *(const f32x4*)(wg + col + 4 * n) * (*(const f32x4*)(wsc + (b * 9216u + col + 4 * n)) + 1.0f); if (WG2) { w2[n] = *(const f32x4*)(wg2 + col + 4 * n); wv[n] = wv[n] * w2[n]; } }
;             }
;             f32x4 xq[2][2][2];
;     ...
;             constexpr bool DEEP = !LAZY && !WG2;
;             if (DEEP) RES_LD(0, 0);
; #pragma unroll
;             for (int pp = 0; pp < 4; ++pp) {
;                 if (DEEP) { if (pp < 3) RES_LD((pp + 1) & 1, pp + 1); } else RES_LD(pp & 1, pp);
; #pragma unroll
;                 for (int j = 0; j < 2; ++j) { const int i_ = 2 * pp + j, ai = i_ >> 2, m = i_ & 3; const unsigned off = (row0 + ai * HALF + m * 16) * 1024u + col;
;                     const f32x4 xi0 = xq[pp & 1][j][0], xi1 = xq[pp & 1][j][1];
;                     f32x4 xo0 = gv[0] * acc[ai][bj][m][0], xo1 = gv[1] * acc[ai][bj][m][1];
;                     if (LAZY) { xo0 = xo0 + xi0 * lg[0] * rl[ai][m]; xo1 = xo1 + xi1 * lg[1] * rl[ai][m]; } else { xo0 = xo0 + xi0; xo1 = xo1 + xi1; }
;                     *(f32x4*)(xout + off) = xo0; *(f32x4*)(xout + off + 4) = xo1;
;                     if (aout) { const f32x4 a0 = xo0 * wv[0], a1 = xo1 * wv[1]; u32x4 w; w.x = cvt_pk_bf16(a0[0], a0[1]); w.y = cvt_pk_bf16(a0[2], a0[3]); w.z = cvt_pk_bf16(a1[0], a1[1]); w.w = cvt_pk_bf16(a1[2], a1[3]);
;                         *(u32x4*)(aout + off) = w;
;                         sq[ai][m] += ((xo0[0] * xo0[0] + xo0[1] * xo0[1]) + (xo0[2] * xo0[2] + xo0[3] * xo0[3])) + ((xo1[0] * xo1[0] + xo1[1] * xo1[1]) + (xo1[2] * xo1[2] + xo1[3] * xo1[3]));
.LBB0_405:
	v_or_b32_e32 v208, 0x80, v192
	v_add_u32_e32 v176, s41, v208
	v_lshl_add_u64 v[130:131], v[176:177], 2, s[42:43]
	global_load_dwordx4 v[136:139], v[130:131], off nt
	v_mov_b32_e32 v192, 0
	v_mov_b32_e32 v128, 1.0
	s_and_b64 vcc, exec, s[8:9]
	v_lshl_add_u64 v[144:145], v[176:177], 2, s[44:45]
	v_mov_b32_e32 v132, 1.0
	v_mov_b32_e32 v133, 1.0
	v_mov_b32_e32 v134, 1.0
	v_mov_b32_e32 v135, 1.0
	v_mov_b32_e32 v194, 0
	v_mov_b32_e32 v195, 0
	v_mov_b32_e32 v196, 0
	v_mov_b32_e32 v197, 0
	s_cbranch_vccnz .LBB0_407
	global_load_dwordx4 v[132:135], v[190:191], off offset:512 nt
	global_load_dwordx4 v[140:143], v[144:145], off nt
	s_waitcnt vmcnt(0)
	v_pk_add_f32 v[142:143], v[142:143], 1.0 op_sel_hi:[1,0]
	v_pk_add_f32 v[140:141], v[140:141], 1.0 op_sel_hi:[1,0]
	v_pk_mul_f32 v[142:143], v[134:135], v[142:143]
	v_pk_mul_f32 v[140:141], v[132:133], v[140:141]
	global_load_dwordx4 v[132:135], v[188:189], off offset:512 nt
	s_waitcnt vmcnt(0)
	v_pk_mul_f32 v[196:197], v[134:135], v[142:143]
	v_pk_mul_f32 v[194:195], v[132:133], v[140:141]
.LBB0_407:
	global_load_dwordx4 v[140:143], v[130:131], off offset:16 nt
	s_and_b64 vcc, exec, s[8:9]
	v_mov_b32_e32 v129, 1.0
	v_mov_b32_e32 v130, 1.0
	v_mov_b32_e32 v131, 1.0
	v_mov_b32_e32 v193, 0
	v_mov_b32_e32 v198, 0
	v_mov_b32_e32 v199, 0
	s_cbranch_vccnz .LBB0_409
	global_load_dwordx4 v[128:131], v[190:191], off offset:528 nt
	s_nop 0
	global_load_dwordx4 v[144:147], v[144:145], off offset:16 nt
	s_waitcnt vmcnt(0)
	v_pk_add_f32 v[146:147], v[146:147], 1.0 op_sel_hi:[1,0]
	v_pk_add_f32 v[144:145], v[144:145], 1.0 op_sel_hi:[1,0]
	v_pk_mul_f32 v[146:147], v[130:131], v[146:147]
	v_pk_mul_f32 v[144:145], v[128:129], v[144:145]
	global_load_dwordx4 v[128:131], v[188:189], off offset:528 nt
	s_waitcnt vmcnt(0)
	v_pk_mul_f32 v[198:199], v[130:131], v[146:147]
	v_pk_mul_f32 v[192:193], v[128:129], v[144:145]
.LBB0_409:
	v_add_u32_e32 v176, v208, v153
	v_lshlrev_b64 v[206:207], 2, v[176:177]
	v_lshl_add_u64 v[144:145], s[38:39], 0, v[206:207]
	v_mov_b32_e32 v205, v177
	v_add_u32_e32 v204, 0x4000, v176
	global_load_dwordx4 v[210:213], v[144:145], off nt
	global_load_dwordx4 v[232:235], v[144:145], off offset:16 nt
	v_lshl_add_u64 v[148:149], v[204:205], 2, s[38:39]
	global_load_dwordx4 v[144:147], v[148:149], off offset:16 nt
	s_nop 0
	global_load_dwordx4 v[148:151], v[148:149], off nt
	s_mov_b32 s41, s40
	s_mov_b32 s42, s40
	s_mov_b32 s43, s40
	s_waitcnt vmcnt(4)
	v_pk_mul_f32 v[190:191], s[42:43], v[142:143]
	v_pk_mul_f32 v[188:189], s[40:41], v[140:141]
	v_pk_mul_f32 v[200:201], s[42:43], v[138:139]
	v_pk_mul_f32 v[202:203], s[40:41], v[136:137]
	s_and_b64 vcc, exec, s[8:9]
	v_lshl_add_u64 v[206:207], s[36:37], 0, v[206:207]
	s_waitcnt vmcnt(3)
	v_pk_fma_f32 v[142:143], v[118:119], v[200:201], v[212:213]
	v_pk_fma_f32 v[140:141], v[116:117], v[202:203], v[210:211]
	s_waitcnt vmcnt(2)
	v_pk_fma_f32 v[138:139], v[114:115], v[190:191], v[234:235]
	v_pk_fma_f32 v[136:137], v[112:113], v[188:189], v[232:233]
	global_store_dwordx4 v[206:207], v[140:143], off
	global_store_dwordx4 v[206:207], v[136:139], off offset:16
	s_cbranch_vccnz .LBB0_411
	v_pk_mul_f32 v[206:207], v[196:197], v[142:143]
	v_pk_mul_f32 v[210:211], v[194:195], v[140:141]
	v_pk_mul_f32 v[212:213], v[192:193], v[136:137]
	v_cvt_pk_bf16_f32 v210, v210, v211
	v_cvt_pk_bf16_f32 v211, v206, v207
	v_lshl_add_u64 v[206:207], v[176:177], 1, s[34:35]
	v_pk_mul_f32 v[214:215], v[198:199], v[138:139]
	v_cvt_pk_bf16_f32 v212, v212, v213
	v_mov_b32_e32 v232, v140
	v_cvt_pk_bf16_f32 v213, v214, v215
	global_store_dwordx4 v[206:207], v[210:213], off
	v_pk_mul_f32 v[206:207], v[134:135], v[142:143]
	v_pk_mul_f32 v[214:215], v[128:129], v[136:137]
	v_pk_mul_f32 v[210:211], v[132:133], v[140:141]
	v_pk_mul_f32 v[212:213], v[130:131], v[138:139]
	v_mov_b32_e32 v233, v210
	v_mov_b32_e32 v210, v141
	v_pk_mul_f32 v[140:141], v[210:211], v[210:211]
	v_mov_b32_e32 v211, v206
	v_mov_b32_e32 v206, v143
	v_mov_b32_e32 v210, v142
	v_pk_mul_f32 v[142:143], v[206:207], v[206:207]
	v_pk_fma_f32 v[140:141], v[232:233], v[232:233], v[140:141]
	v_pk_fma_f32 v[142:143], v[210:211], v[210:211], v[142:143]
	s_nop 0
	v_pk_add_f32 v[140:141], v[140:141], v[142:143]
	v_mov_b32_e32 v143, v214
	v_mov_b32_e32 v214, v137
	v_mov_b32_e32 v142, v136
	v_pk_mul_f32 v[136:137], v[214:215], v[214:215]
	s_nop 0
	v_pk_fma_f32 v[136:137], v[142:143], v[142:143], v[136:137]
	v_mov_b32_e32 v143, v212
	v_mov_b32_e32 v212, v139
	v_mov_b32_e32 v142, v138
	v_pk_mul_f32 v[138:139], v[212:213], v[212:213]
	s_nop 0
	v_pk_fma_f32 v[138:139], v[142:143], v[142:143], v[138:139]
	s_nop 0
	v_pk_add_f32 v[136:137], v[136:137], v[138:139]
	s_nop 0
	v_pk_add_f32 v[136:137], v[140:141], v[136:137]
	s_nop 0
	v_pk_add_f32 v[154:155], v[154:155], v[136:137]

; __device__ __forceinline__ unsigned cvt_pk_bf16(float lo, float hi) { unsigned r; asm volatile("v_cvt_pk_bf16_f32 %0, %1, %2" : "=v"(r) : "v"(lo), "v"(hi)); return r; }
; #define RES_LD(buf, pp) do { _Pragma("unroll") for (int j = 0; j < 2; ++j) { const int i_ = 2 * (pp) + j; const unsigned off_ = (row0 + (i_ >> 2) * HALF + (i_ & 3) * 16) * 1024u + col; \
;                 xq[buf][j][0] = *(const f32x4*)(xin + off_); xq[buf][j][1] = *(const f32x4*)(xin + off_ + 4); } } while (0)
;     static __device__ __forceinline__ void run(const f32x4 (&acc)[2][2][4][2], const Unit& u, int wr, int wc, int fr, int fq, const float* xin, float* xout, const float* gate, float gs, const float* lazy_ssq, const float* lazy_g, ...
;     ...
;             constexpr bool DEEP = !LAZY && !WG2;
;             if (DEEP) RES_LD(0, 0);
; #pragma unroll
;             for (int pp = 0; pp < 4; ++pp) {
;                 if (DEEP) { if (pp < 3) RES_LD((pp + 1) & 1, pp + 1); } else RES_LD(pp & 1, pp);
; #pragma unroll
;                 for (int j = 0; j < 2; ++j) { const int i_ = 2 * pp + j, ai = i_ >> 2, m = i_ & 3; const unsigned off = (row0 + ai * HALF + m * 16) * 1024u + col;
;                     const f32x4 xi0 = xq[pp & 1][j][0], xi1 = xq[pp & 1][j][1];
;                     f32x4 xo0 = gv[0] * acc[ai][bj][m][0], xo1 = gv[1] * acc[ai][bj][m][1];
;                     if (LAZY) { xo0 = xo0 + xi0 * lg[0] * rl[ai][m]; xo1 = xo1 + xi1 * lg[1] * rl[ai][m]; } else { xo0 = xo0 + xi0; xo1 = xo1 + xi1; }
;                     *(f32x4*)(xout + off) = xo0; *(f32x4*)(xout + off + 4) = xo1;
;                     if (aout) { const f32x4 a0 = xo0 * wv[0], a1 = xo1 * wv[1]; u32x4 w; w.x = cvt_pk_bf16(a0[0], a0[1]); w.y = cvt_pk_bf16(a0[2], a0[3]); w.z = cvt_pk_bf16(a1[0], a1[1]); w.w = cvt_pk_bf16(a1[2], a1[3]);
;                         *(u32x4*)(aout + off) = w;
;                         sq[ai][m] += ((xo0[0] * xo0[0] + xo0[1] * xo0[1]) + (xo0[2] * xo0[2] + xo0[3] * xo0[3])) + ((xo1[0] * xo1[0] + xo1[1] * xo1[1]) + (xo1[2] * xo1[2] + xo1[3] * xo1[3]));
;                         if (WG2) { const f32x4 b0 = xo0 * w2[0], b1 = xo1 * w2[1]; sqb[ai][m] += ((b0[0] * b0[0] + b0[1] * b0[1]) + (b0[2] * b0[2] + b0[3] * b0[3])) + ((b1[0] * b1[0] + b1[1] * b1[1]) + (b1[2] * b1[2] + b1[3] * b1[3])); } } }
.LBB0_413:
	v_add_u32_e32 v206, 0x8000, v176
	v_mov_b32_e32 v207, v177
	v_lshlrev_b64 v[148:149], 2, v[206:207]
	v_lshl_add_u64 v[136:137], s[38:39], 0, v[148:149]
	v_add_u32_e32 v204, 0xc000, v176
	v_mov_b32_e32 v205, v177
	global_load_dwordx4 v[144:147], v[136:137], off nt
	global_load_dwordx4 v[210:213], v[136:137], off offset:16 nt
	v_lshl_add_u64 v[140:141], v[204:205], 2, s[38:39]
	global_load_dwordx4 v[136:139], v[140:141], off offset:16 nt
	s_nop 0
	global_load_dwordx4 v[140:143], v[140:141], off nt
	s_and_b64 vcc, exec, s[8:9]
	v_lshl_add_u64 v[214:215], s[36:37], 0, v[148:149]
	s_waitcnt vmcnt(3)
	v_pk_fma_f32 v[150:151], v[86:87], v[200:201], v[146:147]
	v_pk_fma_f32 v[148:149], v[84:85], v[202:203], v[144:145]
	s_waitcnt vmcnt(2)
	v_pk_fma_f32 v[146:147], v[82:83], v[190:191], v[212:213]
	v_pk_fma_f32 v[144:145], v[80:81], v[188:189], v[210:211]
	global_store_dwordx4 v[214:215], v[148:151], off
	global_store_dwordx4 v[214:215], v[144:147], off offset:16
	s_cbranch_vccnz .LBB0_415
	v_pk_mul_f32 v[210:211], v[194:195], v[148:149]
	v_pk_mul_f32 v[212:213], v[196:197], v[150:151]
	v_cvt_pk_bf16_f32 v210, v210, v211
	v_lshl_add_u64 v[206:207], v[206:207], 1, s[34:35]
	v_cvt_pk_bf16_f32 v211, v212, v213
	v_pk_mul_f32 v[214:215], v[198:199], v[146:147]
	v_pk_mul_f32 v[232:233], v[192:193], v[144:145]
	s_nop 0
	v_cvt_pk_bf16_f32 v212, v232, v233
	v_cvt_pk_bf16_f32 v213, v214, v215
	global_store_dwordx4 v[206:207], v[210:213], off
	v_pk_mul_f32 v[206:207], v[134:135], v[150:151]
	v_mov_b32_e32 v232, v148
	v_pk_mul_f32 v[210:211], v[132:133], v[148:149]
	v_pk_mul_f32 v[214:215], v[128:129], v[144:145]
	v_mov_b32_e32 v233, v210
	v_mov_b32_e32 v210, v149
	v_pk_mul_f32 v[148:149], v[210:211], v[210:211]
	v_mov_b32_e32 v211, v206
	v_mov_b32_e32 v206, v151
	v_mov_b32_e32 v210, v150
	v_pk_mul_f32 v[150:151], v[206:207], v[206:207]
	v_pk_fma_f32 v[148:149], v[232:233], v[232:233], v[148:149]
	v_pk_fma_f32 v[150:151], v[210:211], v[210:211], v[150:151]
	v_pk_mul_f32 v[212:213], v[130:131], v[146:147]
	v_pk_add_f32 v[148:149], v[148:149], v[150:151]
	v_mov_b32_e32 v151, v214
	v_mov_b32_e32 v214, v145
	v_mov_b32_e32 v150, v144
	v_pk_mul_f32 v[144:145], v[214:215], v[214:215]
	s_nop 0
	v_pk_fma_f32 v[144:145], v[150:151], v[150:151], v[144:145]
	v_mov_b32_e32 v151, v212
	v_mov_b32_e32 v212, v147
	v_mov_b32_e32 v150, v146
	v_pk_mul_f32 v[146:147], v[212:213], v[212:213]
	s_nop 0
	v_pk_fma_f32 v[146:147], v[150:151], v[150:151], v[146:147]
	s_nop 0
	v_pk_add_f32 v[144:145], v[144:145], v[146:147]
	s_nop 0
	v_pk_add_f32 v[144:145], v[148:149], v[144:145]
	s_nop 0
	v_pk_add_f32 v[158:159], v[158:159], v[144:145]

; __device__ __forceinline__ unsigned cvt_pk_bf16(float lo, float hi) { unsigned r; asm volatile("v_cvt_pk_bf16_f32 %0, %1, %2" : "=v"(r) : "v"(lo), "v"(hi)); return r; }
; #define RES_LD(buf, pp) do { _Pragma("unroll") for (int j = 0; j < 2; ++j) { const int i_ = 2 * (pp) + j; const unsigned off_ = (row0 + (i_ >> 2) * HALF + (i_ & 3) * 16) * 1024u + col; \
;                 xq[buf][j][0] = *(const f32x4*)(xin + off_); xq[buf][j][1] = *(const f32x4*)(xin + off_ + 4); } } while (0)
;     static __device__ __forceinline__ void run(const f32x4 (&acc)[2][2][4][2], const Unit& u, int wr, int wc, int fr, int fq, const float* xin, float* xout, const float* gate, float gs, const float* lazy_ssq, const float* lazy_g, ...
;     ...
;             constexpr bool DEEP = !LAZY && !WG2;
;             if (DEEP) RES_LD(0, 0);
; #pragma unroll
;             for (int pp = 0; pp < 4; ++pp) {
;                 if (DEEP) { if (pp < 3) RES_LD((pp + 1) & 1, pp + 1); } else RES_LD(pp & 1, pp);
; #pragma unroll
;                 for (int j = 0; j < 2; ++j) { const int i_ = 2 * pp + j, ai = i_ >> 2, m = i_ & 3; const unsigned off = (row0 + ai * HALF + m * 16) * 1024u + col;
;                     const f32x4 xi0 = xq[pp & 1][j][0], xi1 = xq[pp & 1][j][1];
;                     f32x4 xo0 = gv[0] * acc[ai][bj][m][0], xo1 = gv[1] * acc[ai][bj][m][1];
;                     if (LAZY) { xo0 = xo0 + xi0 * lg[0] * rl[ai][m]; xo1 = xo1 + xi1 * lg[1] * rl[ai][m]; } else { xo0 = xo0 + xi0; xo1 = xo1 + xi1; }
;                     *(f32x4*)(xout + off) = xo0; *(f32x4*)(xout + off + 4) = xo1;
;                     if (aout) { const f32x4 a0 = xo0 * wv[0], a1 = xo1 * wv[1]; u32x4 w; w.x = cvt_pk_bf16(a0[0], a0[1]); w.y = cvt_pk_bf16(a0[2], a0[3]); w.z = cvt_pk_bf16(a1[0], a1[1]); w.w = cvt_pk_bf16(a1[2], a1[3]);
;                         *(u32x4*)(aout + off) = w;
;                         sq[ai][m] += ((xo0[0] * xo0[0] + xo0[1] * xo0[1]) + (xo0[2] * xo0[2] + xo0[3] * xo0[3])) + ((xo1[0] * xo1[0] + xo1[1] * xo1[1]) + (xo1[2] * xo1[2] + xo1[3] * xo1[3]));
;                         if (WG2) { const f32x4 b0 = xo0 * w2[0], b1 = xo1 * w2[1]; sqb[ai][m] += ((b0[0] * b0[0] + b0[1] * b0[1]) + (b0[2] * b0[2] + b0[3] * b0[3])) + ((b1[0] * b1[0] + b1[1] * b1[1]) + (b1[2] * b1[2] + b1[3] * b1[3])); } } }
.LBB0_417:
	v_add_u32_e32 v204, v173, v208
	v_mov_b32_e32 v205, v177
	v_lshl_add_u64 v[136:137], v[204:205], 2, s[38:39]
	global_load_dwordx4 v[144:147], v[136:137], off offset:16 nt
	global_load_dwordx4 v[148:151], v[136:137], off nt
	v_add_u32_e32 v136, 0x4000, v204
	v_mov_b32_e32 v137, v177
	v_lshl_add_u64 v[140:141], v[136:137], 2, s[38:39]
	global_load_dwordx4 v[136:139], v[140:141], off offset:16 nt
	s_nop 0
	global_load_dwordx4 v[140:143], v[140:141], off nt
	v_add_u32_e32 v206, 0x20000, v176
	v_mov_b32_e32 v207, v177
	v_lshl_add_u64 v[208:209], v[206:207], 2, s[36:37]
	s_and_b64 vcc, exec, s[8:9]
	s_waitcnt vmcnt(3)
	v_pk_fma_f32 v[146:147], v[50:51], v[190:191], v[146:147]
	s_waitcnt vmcnt(2)
	v_pk_fma_f32 v[150:151], v[54:55], v[200:201], v[150:151]
	v_pk_fma_f32 v[148:149], v[52:53], v[202:203], v[148:149]
	v_pk_fma_f32 v[144:145], v[48:49], v[188:189], v[144:145]
	global_store_dwordx4 v[208:209], v[148:151], off
	global_store_dwordx4 v[208:209], v[144:147], off offset:16
	s_cbranch_vccnz .LBB0_419
	v_pk_mul_f32 v[208:209], v[194:195], v[148:149]
	v_pk_mul_f32 v[210:211], v[196:197], v[150:151]
	v_cvt_pk_bf16_f32 v208, v208, v209
	v_lshl_add_u64 v[206:207], v[206:207], 1, s[34:35]
	v_cvt_pk_bf16_f32 v209, v210, v211
	v_pk_mul_f32 v[212:213], v[198:199], v[146:147]
	v_pk_mul_f32 v[214:215], v[192:193], v[144:145]
	s_nop 0
	v_cvt_pk_bf16_f32 v210, v214, v215
	v_cvt_pk_bf16_f32 v211, v212, v213
	global_store_dwordx4 v[206:207], v[208:211], off
	v_pk_mul_f32 v[206:207], v[134:135], v[150:151]
	v_mov_b32_e32 v214, v148
	v_pk_mul_f32 v[208:209], v[132:133], v[148:149]
	v_pk_mul_f32 v[212:213], v[128:129], v[144:145]
	v_mov_b32_e32 v215, v208
	v_mov_b32_e32 v208, v149
	v_pk_mul_f32 v[148:149], v[208:209], v[208:209]
	v_mov_b32_e32 v209, v206
	v_mov_b32_e32 v206, v151
	v_mov_b32_e32 v208, v150
	v_pk_mul_f32 v[150:151], v[206:207], v[206:207]
	v_pk_fma_f32 v[148:149], v[214:215], v[214:215], v[148:149]
	v_pk_fma_f32 v[150:151], v[208:209], v[208:209], v[150:151]
	v_pk_mul_f32 v[210:211], v[130:131], v[146:147]
	v_pk_add_f32 v[148:149], v[148:149], v[150:151]
	v_mov_b32_e32 v151, v212
	v_mov_b32_e32 v212, v145
	v_mov_b32_e32 v150, v144
	v_pk_mul_f32 v[144:145], v[212:213], v[212:213]
	s_nop 0
	v_pk_fma_f32 v[144:145], v[150:151], v[150:151], v[144:145]
	v_mov_b32_e32 v151, v210
	v_mov_b32_e32 v210, v147
	v_mov_b32_e32 v150, v146
	v_pk_mul_f32 v[146:147], v[210:211], v[210:211]
	s_nop 0
	v_pk_fma_f32 v[146:147], v[150:151], v[150:151], v[146:147]
	s_nop 0
	v_pk_add_f32 v[144:145], v[144:145], v[146:147]
	s_nop 0
	v_pk_add_f32 v[144:145], v[148:149], v[144:145]
	s_nop 0
	v_pk_add_f32 v[180:181], v[180:181], v[144:145]

; __device__ __forceinline__ unsigned cvt_pk_bf16(float lo, float hi) { unsigned r; asm volatile("v_cvt_pk_bf16_f32 %0, %1, %2" : "=v"(r) : "v"(lo), "v"(hi)); return r; }
; #define RES_LD(buf, pp) do { _Pragma("unroll") for (int j = 0; j < 2; ++j) { const int i_ = 2 * (pp) + j; const unsigned off_ = (row0 + (i_ >> 2) * HALF + (i_ & 3) * 16) * 1024u + col; \
;                 xq[buf][j][0] = *(const f32x4*)(xin + off_); xq[buf][j][1] = *(const f32x4*)(xin + off_ + 4); } } while (0)
;     static __device__ __forceinline__ void run(const f32x4 (&acc)[2][2][4][2], const Unit& u, int wr, int wc, int fr, int fq, const float* xin, float* xout, const float* gate, float gs, const float* lazy_ssq, const float* lazy_g, ...
;     ...
;             constexpr bool DEEP = !LAZY && !WG2;
;             if (DEEP) RES_LD(0, 0);
; #pragma unroll
;             for (int pp = 0; pp < 4; ++pp) {
;                 if (DEEP) { if (pp < 3) RES_LD((pp + 1) & 1, pp + 1); } else RES_LD(pp & 1, pp);
; #pragma unroll
;                 for (int j = 0; j < 2; ++j) { const int i_ = 2 * pp + j, ai = i_ >> 2, m = i_ & 3; const unsigned off = (row0 + ai * HALF + m * 16) * 1024u + col;
;                     const f32x4 xi0 = xq[pp & 1][j][0], xi1 = xq[pp & 1][j][1];
;                     f32x4 xo0 = gv[0] * acc[ai][bj][m][0], xo1 = gv[1] * acc[ai][bj][m][1];
;                     if (LAZY) { xo0 = xo0 + xi0 * lg[0] * rl[ai][m]; xo1 = xo1 + xi1 * lg[1] * rl[ai][m]; } else { xo0 = xo0 + xi0; xo1 = xo1 + xi1; }
;                     *(f32x4*)(xout + off) = xo0; *(f32x4*)(xout + off + 4) = xo1;
;                     if (aout) { const f32x4 a0 = xo0 * wv[0], a1 = xo1 * wv[1]; u32x4 w; w.x = cvt_pk_bf16(a0[0], a0[1]); w.y = cvt_pk_bf16(a0[2], a0[3]); w.z = cvt_pk_bf16(a1[0], a1[1]); w.w = cvt_pk_bf16(a1[2], a1[3]);
;                         *(u32x4*)(aout + off) = w;
;                         sq[ai][m] += ((xo0[0] * xo0[0] + xo0[1] * xo0[1]) + (xo0[2] * xo0[2] + xo0[3] * xo0[3])) + ((xo1[0] * xo1[0] + xo1[1] * xo1[1]) + (xo1[2] * xo1[2] + xo1[3] * xo1[3]));
;                         if (WG2) { const f32x4 b0 = xo0 * w2[0], b1 = xo1 * w2[1]; sqb[ai][m] += ((b0[0] * b0[0] + b0[1] * b0[1]) + (b0[2] * b0[2] + b0[3] * b0[3])) + ((b1[0] * b1[0] + b1[1] * b1[1]) + (b1[2] * b1[2] + b1[3] * b1[3])); } } }
.LBB0_421:
	s_nop 0
	v_add_u32_e32 v136, 0x8000, v204
	v_mov_b32_e32 v137, v177
	v_lshl_add_u64 v[136:137], v[136:137], 2, s[38:39]
	global_load_dwordx4 v[144:147], v[136:137], off offset:16 nt
	global_load_dwordx4 v[148:151], v[136:137], off nt
	v_add_u32_e32 v136, 0xc000, v204
	v_mov_b32_e32 v137, v177
	v_lshl_add_u64 v[140:141], v[136:137], 2, s[38:39]
	global_load_dwordx4 v[136:139], v[140:141], off offset:16 nt
	s_nop 0
	global_load_dwordx4 v[140:143], v[140:141], off nt
	v_add_u32_e32 v204, 0x28000, v176
	v_mov_b32_e32 v205, v177
	v_lshl_add_u64 v[206:207], v[204:205], 2, s[36:37]
	s_and_b64 vcc, exec, s[8:9]
	s_waitcnt vmcnt(3)
	v_pk_fma_f32 v[146:147], v[18:19], v[190:191], v[146:147]
	s_waitcnt vmcnt(2)
	v_pk_fma_f32 v[150:151], v[22:23], v[200:201], v[150:151]
	v_pk_fma_f32 v[148:149], v[20:21], v[202:203], v[148:149]
	v_pk_fma_f32 v[144:145], v[16:17], v[188:189], v[144:145]
	global_store_dwordx4 v[206:207], v[148:151], off
	global_store_dwordx4 v[206:207], v[144:147], off offset:16
	s_cbranch_vccnz .LBB0_423
	v_pk_mul_f32 v[206:207], v[194:195], v[148:149]
	v_pk_mul_f32 v[208:209], v[196:197], v[150:151]
	v_cvt_pk_bf16_f32 v206, v206, v207
	v_lshl_add_u64 v[204:205], v[204:205], 1, s[34:35]
	v_cvt_pk_bf16_f32 v207, v208, v209
	v_pk_mul_f32 v[210:211], v[198:199], v[146:147]
	v_pk_mul_f32 v[212:213], v[192:193], v[144:145]
	s_nop 0
	v_cvt_pk_bf16_f32 v208, v212, v213
	v_cvt_pk_bf16_f32 v209, v210, v211
	global_store_dwordx4 v[204:205], v[206:209], off
	v_pk_mul_f32 v[204:205], v[134:135], v[150:151]
	v_mov_b32_e32 v212, v148
	v_pk_mul_f32 v[206:207], v[132:133], v[148:149]
	v_pk_mul_f32 v[210:211], v[128:129], v[144:145]
	v_mov_b32_e32 v213, v206
	v_mov_b32_e32 v206, v149
	v_pk_mul_f32 v[148:149], v[206:207], v[206:207]
	v_mov_b32_e32 v207, v204
	v_mov_b32_e32 v204, v151
	v_mov_b32_e32 v206, v150
	v_pk_mul_f32 v[150:151], v[204:205], v[204:205]
	v_pk_fma_f32 v[148:149], v[212:213], v[212:213], v[148:149]
	v_pk_fma_f32 v[150:151], v[206:207], v[206:207], v[150:151]
	v_pk_mul_f32 v[208:209], v[130:131], v[146:147]
	v_pk_add_f32 v[148:149], v[148:149], v[150:151]
	v_mov_b32_e32 v151, v210
	v_mov_b32_e32 v210, v145
	v_mov_b32_e32 v150, v144
	v_pk_mul_f32 v[144:145], v[210:211], v[210:211]
	s_nop 0
	v_pk_fma_f32 v[144:145], v[150:151], v[150:151], v[144:145]
	v_mov_b32_e32 v151, v208
	v_mov_b32_e32 v208, v147
	v_mov_b32_e32 v150, v146
	v_pk_mul_f32 v[146:147], v[208:209], v[208:209]
	s_nop 0
	v_pk_fma_f32 v[146:147], v[150:151], v[150:151], v[146:147]
	s_nop 0
	v_pk_add_f32 v[144:145], v[144:145], v[146:147]
	s_nop 0
	v_pk_add_f32 v[144:145], v[148:149], v[144:145]
	s_nop 0
	v_pk_add_f32 v[184:185], v[184:185], v[144:145]

;     __device__ __forceinline__ unsigned u(int i) const { return (unsigned)__builtin_amdgcn_readfirstlane((int)d[i]); }
;     __device__ __forceinline__ unsigned u(int i) const { return (unsigned)__builtin_amdgcn_readfirstlane((int)d[i]); }
;     static __device__ __forceinline__ void run(const f32x4 (&acc)[2][2][4][2], const Unit& u, int wr, int wc, int fr, int fq, const float* xin, float* xout, const float* gate, float gs, const float* lazy_ssq, const float* lazy_g, ...
;         const unsigned b = (unsigned)(u.pm * BM) >> 13; const unsigned row0 = u.pm * BM + wr * 64 + fr; const unsigned col0 = u.pn * BM + wc * 32 + 8 * fq;
;         float rl[2][4], sq[2][4], sqb[2][4];
; #pragma unroll
;         for (int ai = 0; ai < 2; ++ai)
; #pragma unroll
;             for (int m = 0; m < 4; ++m) { rl[ai][m] = LAZY ? __builtin_amdgcn_rsqf(lazy_ssq[row0 + ai * HALF + m * 16] * (1.0f / 1024.0f) + 1e-6f) : 1.0f; sq[ai][m] = 0.f; sqb[ai][m] = 0.f; }
; #pragma unroll
;         for (int bj = 0; bj < 2; ++bj) {
;             const unsigned col = col0 + bj * HALF;
;             f32x4 gv[2], lg[2], wv[2], w2[2];
; #pragma unroll
;             for (int n = 0; n < 2; ++n) {
;                 gv[n] = *(const f32x4*)(gate + (b * 9216u + col + 4 * n)) * gs;
;                 lg[n] = (f32x4){1.f, 1.f, 1.f, 1.f}; if (LAZY) lg[n] = *(const f32x4*)(lazy_g + col + 4 * n);
;                 wv[n] = (f32x4){0.f, 0.f, 0.f, 0.f}; w2[n] = (f32x4){1.f, 1.f, 1.f, 1.f};
;                 if (aout) { wv[n] = *(const f32x4*)(wg + col + 4 * n) * (*(const f32x4*)(wsc + (b * 9216u + col + 4 * n)) + 1.0f); if (WG2) { w2[n] = *(const f32x4*)(wg2 + col + 4 * n); wv[n] = wv[n] * w2[n]; } }
.LBB0_480:
	s_and_b64 vcc, exec, s[8:9]
	s_cbranch_vccz .LBB0_544
	s_cmp_gt_i32 s66, 0
	s_mov_b64 s[8:9], -1
	s_cbranch_scc0 .LBB0_542
	v_readlane_b32 s8, v251, 31
	s_bfe_u32 s37, s63, 0x130005
	s_mulk_i32 s37, 0x2400
	v_mov_b32_e32 v128, s8
	ds_read2_b64 v[128:131], v128 offset1:1
	v_readlane_b32 s8, v251, 32
	v_mov_b32_e32 v181, v177
	v_mov_b32_e32 v182, 0
	v_mov_b32_e32 v183, v182
	s_waitcnt lgkmcnt(0)
	v_readfirstlane_b32 s34, v128
	v_mov_b32_e32 v128, s86
	v_readfirstlane_b32 s35, v129
	ds_read_b64 v[128:129], v128
	v_readfirstlane_b32 s38, v130
	v_readfirstlane_b32 s39, v131
	v_mov_b32_e32 v184, v182
	v_mov_b32_e32 v185, v182
	s_waitcnt lgkmcnt(0)
	v_readfirstlane_b32 s28, v128
	v_mov_b32_e32 v128, s8
	ds_read_b32 v128, v128
	v_readlane_b32 s8, v251, 28
	v_readfirstlane_b32 s29, v129
	s_waitcnt lgkmcnt(0)
	v_readfirstlane_b32 s36, v128
	v_mov_b32_e32 v128, s8
	ds_read_b128 v[128:131], v128
	s_waitcnt lgkmcnt(0)
	v_readfirstlane_b32 s8, v130
	v_readfirstlane_b32 s26, v128
	s_nop 0
	v_mov_b32_e32 v128, s8
	v_readlane_b32 s8, v251, 29
	v_readfirstlane_b32 s9, v131
	v_readfirstlane_b32 s27, v129
	v_mov_b32_e32 v130, s8
	ds_read_b64 v[130:131], v130
	v_readlane_b32 s8, v251, 30
	v_mov_b32_e32 v129, s9
	s_lshl_b32 s9, s62, 8
	s_waitcnt lgkmcnt(0)
	v_readfirstlane_b32 s40, v130
	v_mov_b32_e32 v130, s8
	v_readfirstlane_b32 s41, v131
	ds_read_b64 v[130:131], v130
	s_lshl_b32 s8, s64, 5
	s_or_b32 s8, s8, s9
	v_lshl_or_b32 v180, v229, 3, s8
	v_add_u32_e32 v176, s37, v180
	v_lshl_add_u64 v[132:133], v[176:177], 2, s[38:39]
	s_waitcnt lgkmcnt(0)
	v_readfirstlane_b32 s10, v130
	v_readfirstlane_b32 s11, v131
	v_lshl_add_u64 v[174:175], v[180:181], 2, v[128:129]
	global_load_dwordx4 v[128:131], v[132:133], off nt
	s_cmp_lg_u64 s[26:27], 0
	s_cselect_b64 s[30:31], -1, 0
	s_and_b64 vcc, exec, s[30:31]
	v_lshl_add_u64 v[136:137], v[176:177], 2, s[40:41]
	s_cbranch_vccz .LBB0_484
	global_load_dwordx4 v[138:141], v[136:137], off nt
	global_load_dwordx4 v[142:145], v[174:175], off nt
	s_waitcnt vmcnt(0)
	v_pk_add_f32 v[134:135], v[140:141], 1.0 op_sel_hi:[1,0]
	v_pk_add_f32 v[138:139], v[138:139], 1.0 op_sel_hi:[1,0]
	v_pk_mul_f32 v[184:185], v[144:145], v[134:135]
	v_pk_mul_f32 v[182:183], v[142:143], v[138:139]
.LBB0_484:
	global_load_dwordx4 v[132:135], v[132:133], off offset:16 nt
	v_cndmask_b32_e64 v138, 0, 1, s[30:31]
	v_cmp_ne_u32_e64 s[8:9], 1, v138
	s_andn2_b64 vcc, exec, s[30:31]
	s_cbranch_vccnz .LBB0_486
	global_load_dwordx4 v[136:139], v[136:137], off offset:16 nt
	s_nop 0
	global_load_dwordx4 v[140:143], v[174:175], off offset:16 nt
	s_waitcnt vmcnt(0)
	v_pk_add_f32 v[138:139], v[138:139], 1.0 op_sel_hi:[1,0]
	v_pk_add_f32 v[136:137], v[136:137], 1.0 op_sel_hi:[1,0]
	v_pk_mul_f32 v[188:189], v[142:143], v[138:139]
	v_pk_mul_f32 v[186:187], v[140:141], v[136:137]
	s_branch .LBB0_487

; __device__ __forceinline__ unsigned cvt_pk_bf16(float lo, float hi) { unsigned r; asm volatile("v_cvt_pk_bf16_f32 %0, %1, %2" : "=v"(r) : "v"(lo), "v"(hi)); return r; }
; #define RES_LD(buf, pp) do { _Pragma("unroll") for (int j = 0; j < 2; ++j) { const int i_ = 2 * (pp) + j; const unsigned off_ = (row0 + (i_ >> 2) * HALF + (i_ & 3) * 16) * 1024u + col; \
;                 xq[buf][j][0] = *(const f32x4*)(xin + off_); xq[buf][j][1] = *(const f32x4*)(xin + off_ + 4); } } while (0)
;     static __device__ __forceinline__ void run(const f32x4 (&acc)[2][2][4][2], const Unit& u, int wr, int wc, int fr, int fq, const float* xin, float* xout, const float* gate, float gs, const float* lazy_ssq, const float* lazy_g, ...
;     ...
;             constexpr bool DEEP = !LAZY && !WG2;
;             if (DEEP) RES_LD(0, 0);
; #pragma unroll
;             for (int pp = 0; pp < 4; ++pp) {
;                 if (DEEP) { if (pp < 3) RES_LD((pp + 1) & 1, pp + 1); } else RES_LD(pp & 1, pp);
; #pragma unroll
;                 for (int j = 0; j < 2; ++j) { const int i_ = 2 * pp + j, ai = i_ >> 2, m = i_ & 3; const unsigned off = (row0 + ai * HALF + m * 16) * 1024u + col;
;                     const f32x4 xi0 = xq[pp & 1][j][0], xi1 = xq[pp & 1][j][1];
;                     f32x4 xo0 = gv[0] * acc[ai][bj][m][0], xo1 = gv[1] * acc[ai][bj][m][1];
;                     if (LAZY) { xo0 = xo0 + xi0 * lg[0] * rl[ai][m]; xo1 = xo1 + xi1 * lg[1] * rl[ai][m]; } else { xo0 = xo0 + xi0; xo1 = xo1 + xi1; }
;                     *(f32x4*)(xout + off) = xo0; *(f32x4*)(xout + off + 4) = xo1;
;                     if (aout) { const f32x4 a0 = xo0 * wv[0], a1 = xo1 * wv[1]; u32x4 w; w.x = cvt_pk_bf16(a0[0], a0[1]); w.y = cvt_pk_bf16(a0[2], a0[3]); w.z = cvt_pk_bf16(a1[0], a1[1]); w.w = cvt_pk_bf16(a1[2], a1[3]);
;                         *(u32x4*)(aout + off) = w;
;                         sq[ai][m] += ((xo0[0] * xo0[0] + xo0[1] * xo0[1]) + (xo0[2] * xo0[2] + xo0[3] * xo0[3])) + ((xo1[0] * xo1[0] + xo1[1] * xo1[1]) + (xo1[2] * xo1[2] + xo1[3] * xo1[3]));
.LBB0_487:
	s_lshl_b32 s42, s63, 8
	s_lshl_b32 s43, s65, 6
	s_add_i32 s43, s43, s42
	v_or_b32_e32 v172, s43, v230
	v_lshlrev_b32_e32 v207, 10, v172
	v_add_u32_e32 v176, v180, v207
	v_lshlrev_b64 v[204:205], 2, v[176:177]
	s_waitcnt vmcnt(0)
	v_pk_mul_f32 v[196:197], s[36:37], v[128:129] op_sel_hi:[0,1]
	v_lshl_add_u64 v[128:129], s[34:35], 0, v[204:205]
	v_add_u32_e32 v202, 0x4000, v176
	v_mov_b32_e32 v203, v177
	global_load_dwordx4 v[152:155], v[128:129], off offset:16 nt
	global_load_dwordx4 v[156:159], v[128:129], off nt
	v_lshl_add_u64 v[128:129], v[202:203], 2, s[34:35]
	v_add_u32_e32 v200, 0x8000, v176
	v_mov_b32_e32 v201, v177
	v_add_u32_e32 v198, 0xc000, v176
	v_mov_b32_e32 v199, v177
	v_pk_mul_f32 v[190:191], s[36:37], v[132:133] op_sel_hi:[0,1]
	global_load_dwordx4 v[136:139], v[128:129], off offset:16 nt
	global_load_dwordx4 v[144:147], v[128:129], off nt
	v_lshl_add_u64 v[128:129], v[200:201], 2, s[34:35]
	v_lshl_add_u64 v[132:133], v[198:199], 2, s[34:35]
	v_pk_mul_f32 v[192:193], s[36:37], v[134:135] op_sel_hi:[0,1]
	v_pk_mul_f32 v[194:195], s[36:37], v[130:131] op_sel_hi:[0,1]
	global_load_dwordx4 v[140:143], v[128:129], off offset:16 nt
	global_load_dwordx4 v[148:151], v[128:129], off nt
	s_nop 0
	global_load_dwordx4 v[128:131], v[132:133], off offset:16 nt
	s_nop 0
	global_load_dwordx4 v[132:135], v[132:133], off nt
	v_lshl_add_u64 v[204:205], s[28:29], 0, v[204:205]
	s_and_b64 vcc, exec, s[8:9]
	v_mov_b32_e32 v173, 0
	s_waitcnt vmcnt(0)
	v_pk_fma_f32 v[154:155], v[122:123], v[192:193], v[154:155]
	s_waitcnt vmcnt(0)
	v_pk_fma_f32 v[158:159], v[126:127], v[194:195], v[158:159]
	v_pk_fma_f32 v[156:157], v[124:125], v[196:197], v[156:157]
	v_pk_fma_f32 v[152:153], v[120:121], v[190:191], v[152:153]
	global_store_dwordx4 v[204:205], v[156:159], off
	global_store_dwordx4 v[204:205], v[152:155], off offset:16
	v_mov_b32_e32 v204, 0
	s_cbranch_vccnz .LBB0_489
	v_pk_mul_f32 v[210:211], v[184:185], v[158:159]
	v_pk_mul_f32 v[208:209], v[182:183], v[156:157]
	v_pk_mul_f32 v[212:213], v[188:189], v[154:155]
	v_pk_mul_f32 v[214:215], v[186:187], v[152:153]
	v_cvt_pk_bf16_f32 v208, v208, v209
	v_cvt_pk_bf16_f32 v209, v210, v211
	s_nop 0
	v_cvt_pk_bf16_f32 v210, v214, v215
	v_cvt_pk_bf16_f32 v211, v212, v213
	v_lshl_add_u64 v[212:213], v[176:177], 1, s[26:27]
	global_store_dwordx4 v[212:213], v[208:211], off
	s_nop 1
	v_mov_b32_e32 v209, v152
	v_mov_b32_e32 v152, v157
	v_mov_b32_e32 v157, v154
	v_mov_b32_e32 v154, v159
	v_mov_b32_e32 v208, v156
	v_pk_mul_f32 v[152:153], v[152:153], v[152:153]
	v_mov_b32_e32 v156, v158
	v_pk_mul_f32 v[154:155], v[154:155], v[154:155]
	v_pk_fma_f32 v[152:153], v[208:209], v[208:209], v[152:153]
	v_pk_fma_f32 v[154:155], v[156:157], v[156:157], v[154:155]
	s_nop 0
	v_pk_add_f32 v[152:153], v[152:153], v[154:155]
	s_nop 0
	v_add_f32_e32 v173, v152, v153

; __device__ __forceinline__ unsigned cvt_pk_bf16(float lo, float hi) { unsigned r; asm volatile("v_cvt_pk_bf16_f32 %0, %1, %2" : "=v"(r) : "v"(lo), "v"(hi)); return r; }
; #define RES_LD(buf, pp) do { _Pragma("unroll") for (int j = 0; j < 2; ++j) { const int i_ = 2 * (pp) + j; const unsigned off_ = (row0 + (i_ >> 2) * HALF + (i_ & 3) * 16) * 1024u + col; \
;                 xq[buf][j][0] = *(const f32x4*)(xin + off_); xq[buf][j][1] = *(const f32x4*)(xin + off_ + 4); } } while (0)
;     static __device__ __forceinline__ void run(const f32x4 (&acc)[2][2][4][2], const Unit& u, int wr, int wc, int fr, int fq, const float* xin, float* xout, const float* gate, float gs, const float* lazy_ssq, const float* lazy_g, ...
;     ...
;             constexpr bool DEEP = !LAZY && !WG2;
;             if (DEEP) RES_LD(0, 0);
; #pragma unroll
;             for (int pp = 0; pp < 4; ++pp) {
;                 if (DEEP) { if (pp < 3) RES_LD((pp + 1) & 1, pp + 1); } else RES_LD(pp & 1, pp);
; #pragma unroll
;                 for (int j = 0; j < 2; ++j) { const int i_ = 2 * pp + j, ai = i_ >> 2, m = i_ & 3; const unsigned off = (row0 + ai * HALF + m * 16) * 1024u + col;
;                     const f32x4 xi0 = xq[pp & 1][j][0], xi1 = xq[pp & 1][j][1];
;                     f32x4 xo0 = gv[0] * acc[ai][bj][m][0], xo1 = gv[1] * acc[ai][bj][m][1];
;                     if (LAZY) { xo0 = xo0 + xi0 * lg[0] * rl[ai][m]; xo1 = xo1 + xi1 * lg[1] * rl[ai][m]; } else { xo0 = xo0 + xi0; xo1 = xo1 + xi1; }
;                     *(f32x4*)(xout + off) = xo0; *(f32x4*)(xout + off + 4) = xo1;
;                     if (aout) { const f32x4 a0 = xo0 * wv[0], a1 = xo1 * wv[1]; u32x4 w; w.x = cvt_pk_bf16(a0[0], a0[1]); w.y = cvt_pk_bf16(a0[2], a0[3]); w.z = cvt_pk_bf16(a1[0], a1[1]); w.w = cvt_pk_bf16(a1[2], a1[3]);
;                         *(u32x4*)(aout + off) = w;
;                         sq[ai][m] += ((xo0[0] * xo0[0] + xo0[1] * xo0[1]) + (xo0[2] * xo0[2] + xo0[3] * xo0[3])) + ((xo1[0] * xo1[0] + xo1[1] * xo1[1]) + (xo1[2] * xo1[2] + xo1[3] * xo1[3]));
.LBB0_491:
	v_add_u32_e32 v208, 0x20000, v207
	v_add_u32_e32 v202, v208, v180
	v_mov_b32_e32 v203, v177
	v_lshl_add_u64 v[136:137], v[202:203], 2, s[34:35]
	global_load_dwordx4 v[152:155], v[136:137], off offset:16 nt
	global_load_dwordx4 v[156:159], v[136:137], off nt
	v_add_u32_e32 v136, 0x4000, v202
	v_mov_b32_e32 v137, v177
	v_lshl_add_u64 v[144:145], v[136:137], 2, s[34:35]
	global_load_dwordx4 v[136:139], v[144:145], off offset:16 nt
	s_nop 0
	global_load_dwordx4 v[144:147], v[144:145], off nt
	s_waitcnt vmcnt(0)
	v_pk_fma_f32 v[150:151], v[94:95], v[194:195], v[150:151]
	v_pk_fma_f32 v[148:149], v[92:93], v[196:197], v[148:149]
	v_pk_fma_f32 v[142:143], v[90:91], v[192:193], v[142:143]
	v_pk_fma_f32 v[140:141], v[88:89], v[190:191], v[140:141]
	v_lshl_add_u64 v[210:211], v[200:201], 2, s[28:29]
	v_mov_b32_e32 v203, 0
	s_and_b64 vcc, exec, s[8:9]
	v_mov_b32_e32 v205, 0
	global_store_dwordx4 v[210:211], v[148:151], off
	global_store_dwordx4 v[210:211], v[140:143], off offset:16
	s_cbranch_vccnz .LBB0_493
	v_pk_mul_f32 v[212:213], v[184:185], v[150:151]
	v_pk_mul_f32 v[210:211], v[182:183], v[148:149]
	v_lshl_add_u64 v[200:201], v[200:201], 1, s[26:27]
	v_pk_mul_f32 v[214:215], v[188:189], v[142:143]
	v_pk_mul_f32 v[232:233], v[186:187], v[140:141]
	v_cvt_pk_bf16_f32 v210, v210, v211
	v_cvt_pk_bf16_f32 v211, v212, v213
	s_nop 0
	v_cvt_pk_bf16_f32 v212, v232, v233
	v_cvt_pk_bf16_f32 v213, v214, v215
	global_store_dwordx4 v[200:201], v[210:213], off
	v_mov_b32_e32 v201, v140
	v_mov_b32_e32 v140, v149
	v_mov_b32_e32 v149, v142
	v_mov_b32_e32 v142, v151
	v_mov_b32_e32 v200, v148
	v_pk_mul_f32 v[140:141], v[140:141], v[140:141]
	v_mov_b32_e32 v148, v150
	v_pk_mul_f32 v[142:143], v[142:143], v[142:143]
	v_pk_fma_f32 v[140:141], v[200:201], v[200:201], v[140:141]
	v_pk_fma_f32 v[142:143], v[148:149], v[148:149], v[142:143]
	s_nop 0
	v_pk_add_f32 v[140:141], v[140:141], v[142:143]
	s_nop 0
	v_add_f32_e32 v205, v140, v141

; __device__ __forceinline__ unsigned cvt_pk_bf16(float lo, float hi) { unsigned r; asm volatile("v_cvt_pk_bf16_f32 %0, %1, %2" : "=v"(r) : "v"(lo), "v"(hi)); return r; }
; #define RES_LD(buf, pp) do { _Pragma("unroll") for (int j = 0; j < 2; ++j) { const int i_ = 2 * (pp) + j; const unsigned off_ = (row0 + (i_ >> 2) * HALF + (i_ & 3) * 16) * 1024u + col; \
;                 xq[buf][j][0] = *(const f32x4*)(xin + off_); xq[buf][j][1] = *(const f32x4*)(xin + off_ + 4); } } while (0)
;     static __device__ __forceinline__ void run(const f32x4 (&acc)[2][2][4][2], const Unit& u, int wr, int wc, int fr, int fq, const float* xin, float* xout, const float* gate, float gs, const float* lazy_ssq, const float* lazy_g, ...
;     ...
;             constexpr bool DEEP = !LAZY && !WG2;
;             if (DEEP) RES_LD(0, 0);
; #pragma unroll
;             for (int pp = 0; pp < 4; ++pp) {
;                 if (DEEP) { if (pp < 3) RES_LD((pp + 1) & 1, pp + 1); } else RES_LD(pp & 1, pp);
; #pragma unroll
;                 for (int j = 0; j < 2; ++j) { const int i_ = 2 * pp + j, ai = i_ >> 2, m = i_ & 3; const unsigned off = (row0 + ai * HALF + m * 16) * 1024u + col;
;                     const f32x4 xi0 = xq[pp & 1][j][0], xi1 = xq[pp & 1][j][1];
;                     f32x4 xo0 = gv[0] * acc[ai][bj][m][0], xo1 = gv[1] * acc[ai][bj][m][1];
;                     if (LAZY) { xo0 = xo0 + xi0 * lg[0] * rl[ai][m]; xo1 = xo1 + xi1 * lg[1] * rl[ai][m]; } else { xo0 = xo0 + xi0; xo1 = xo1 + xi1; }
;                     *(f32x4*)(xout + off) = xo0; *(f32x4*)(xout + off + 4) = xo1;
;                     if (aout) { const f32x4 a0 = xo0 * wv[0], a1 = xo1 * wv[1]; u32x4 w; w.x = cvt_pk_bf16(a0[0], a0[1]); w.y = cvt_pk_bf16(a0[2], a0[3]); w.z = cvt_pk_bf16(a1[0], a1[1]); w.w = cvt_pk_bf16(a1[2], a1[3]);
;                         *(u32x4*)(aout + off) = w;
;                         sq[ai][m] += ((xo0[0] * xo0[0] + xo0[1] * xo0[1]) + (xo0[2] * xo0[2] + xo0[3] * xo0[3])) + ((xo1[0] * xo1[0] + xo1[1] * xo1[1]) + (xo1[2] * xo1[2] + xo1[3] * xo1[3]));
.LBB0_495:
	s_nop 0
	v_add_u32_e32 v128, 0x8000, v202
	v_mov_b32_e32 v129, v177
	v_lshl_add_u64 v[128:129], v[128:129], 2, s[34:35]
	global_load_dwordx4 v[140:143], v[128:129], off offset:16 nt
	global_load_dwordx4 v[148:151], v[128:129], off nt
	v_add_u32_e32 v128, 0xc000, v202
	v_mov_b32_e32 v129, v177
	v_lshl_add_u64 v[132:133], v[128:129], 2, s[34:35]
	global_load_dwordx4 v[128:131], v[132:133], off offset:16 nt
	s_nop 0
	global_load_dwordx4 v[132:135], v[132:133], off nt
	v_add_u32_e32 v198, 0x20000, v176
	v_mov_b32_e32 v199, v177
	s_waitcnt vmcnt(0)
	v_pk_fma_f32 v[158:159], v[62:63], v[194:195], v[158:159]
	v_pk_fma_f32 v[156:157], v[60:61], v[196:197], v[156:157]
	v_lshl_add_u64 v[200:201], v[198:199], 2, s[28:29]
	v_pk_fma_f32 v[154:155], v[58:59], v[192:193], v[154:155]
	v_pk_fma_f32 v[152:153], v[56:57], v[190:191], v[152:153]
	global_store_dwordx4 v[200:201], v[156:159], off
	global_store_dwordx4 v[200:201], v[152:155], off offset:16
	v_mov_b32_e32 v200, 0
	s_and_b64 vcc, exec, s[8:9]
	v_mov_b32_e32 v201, 0
	s_cbranch_vccnz .LBB0_497
	v_pk_mul_f32 v[212:213], v[184:185], v[158:159]
	v_pk_mul_f32 v[210:211], v[182:183], v[156:157]
	v_lshl_add_u64 v[198:199], v[198:199], 1, s[26:27]
	v_pk_mul_f32 v[214:215], v[188:189], v[154:155]
	v_pk_mul_f32 v[232:233], v[186:187], v[152:153]
	v_cvt_pk_bf16_f32 v210, v210, v211
	v_cvt_pk_bf16_f32 v211, v212, v213
	s_nop 0
	v_cvt_pk_bf16_f32 v212, v232, v233
	v_cvt_pk_bf16_f32 v213, v214, v215
	global_store_dwordx4 v[198:199], v[210:213], off
	v_mov_b32_e32 v199, v152
	v_mov_b32_e32 v152, v157
	v_mov_b32_e32 v157, v154
	v_mov_b32_e32 v154, v159
	v_mov_b32_e32 v198, v156
	v_pk_mul_f32 v[152:153], v[152:153], v[152:153]
	v_mov_b32_e32 v156, v158
	v_pk_mul_f32 v[154:155], v[154:155], v[154:155]
	v_pk_fma_f32 v[152:153], v[198:199], v[198:199], v[152:153]
	v_pk_fma_f32 v[154:155], v[156:157], v[156:157], v[154:155]
	s_nop 0
	v_pk_add_f32 v[152:153], v[152:153], v[154:155]
	s_nop 0
	v_add_f32_e32 v201, v152, v153

;     static __device__ __forceinline__ void run(const f32x4 (&acc)[2][2][4][2], const Unit& u, int wr, int wc, int fr, int fq, const float* xin, float* xout, const float* gate, float gs, const float* lazy_ssq, const float* lazy_g, ...
;     ...
;         for (int bj = 0; bj < 2; ++bj) {
;             const unsigned col = col0 + bj * HALF;
;             f32x4 gv[2], lg[2], wv[2], w2[2];
; #pragma unroll
;             for (int n = 0; n < 2; ++n) {
;                 gv[n] = *(const f32x4*)(gate + (b * 9216u + col + 4 * n)) * gs;
;                 lg[n] = (f32x4){1.f, 1.f, 1.f, 1.f}; if (LAZY) lg[n] = *(const f32x4*)(lazy_g + col + 4 * n);
;                 wv[n] = (f32x4){0.f, 0.f, 0.f, 0.f}; w2[n] = (f32x4){1.f, 1.f, 1.f, 1.f};
;                 if (aout) { wv[n] = *(const f32x4*)(wg + col + 4 * n) * (*(const f32x4*)(wsc + (b * 9216u + col + 4 * n)) + 1.0f); if (WG2) { w2[n] = *(const f32x4*)(wg2 + col + 4 * n); wv[n] = wv[n] * w2[n]; } }
;             }
;             f32x4 xq[2][2][2];
;     ...
;             constexpr bool DEEP = !LAZY && !WG2;
;             if (DEEP) RES_LD(0, 0);
; #pragma unroll
;             for (int pp = 0; pp < 4; ++pp) {
;                 if (DEEP) { if (pp < 3) RES_LD((pp + 1) & 1, pp + 1); } else RES_LD(pp & 1, pp);
; #pragma unroll
;                 for (int j = 0; j < 2; ++j) { const int i_ = 2 * pp + j, ai = i_ >> 2, m = i_ & 3; const unsigned off = (row0 + ai * HALF + m * 16) * 1024u + col;
;                     const f32x4 xi0 = xq[pp & 1][j][0], xi1 = xq[pp & 1][j][1];
;                     f32x4 xo0 = gv[0] * acc[ai][bj][m][0], xo1 = gv[1] * acc[ai][bj][m][1];
;                     if (LAZY) { xo0 = xo0 + xi0 * lg[0] * rl[ai][m]; xo1 = xo1 + xi1 * lg[1] * rl[ai][m]; } else { xo0 = xo0 + xi0; xo1 = xo1 + xi1; }
;                     *(f32x4*)(xout + off) = xo0; *(f32x4*)(xout + off + 4) = xo1;
;                     if (aout) { const f32x4 a0 = xo0 * wv[0], a1 = xo1 * wv[1]; u32x4 w; w.x = cvt_pk_bf16(a0[0], a0[1]); w.y = cvt_pk_bf16(a0[2], a0[3]); w.z = cvt_pk_bf16(a1[0], a1[1]); w.w = cvt_pk_bf16(a1[2], a1[3]);
;                         *(u32x4*)(aout + off) = w;
;                         sq[ai][m] += ((xo0[0] * xo0[0] + xo0[1] * xo0[1]) + (xo0[2] * xo0[2] + xo0[3] * xo0[3])) + ((xo1[0] * xo1[0] + xo1[1] * xo1[1]) + (xo1[2] * xo1[2] + xo1[3] * xo1[3]));
.LBB0_503:
	v_or_b32_e32 v209, 0x80, v180
	v_add_u32_e32 v176, s37, v209
	v_lshl_add_u64 v[130:131], v[176:177], 2, s[38:39]
	global_load_dwordx4 v[140:143], v[130:131], off nt
	v_mov_b32_e32 v180, 0
	s_and_b64 vcc, exec, s[8:9]
	v_lshl_add_u64 v[128:129], v[176:177], 2, s[40:41]
	v_mov_b32_e32 v182, 0
	v_mov_b32_e32 v183, 0
	v_mov_b32_e32 v184, 0
	v_mov_b32_e32 v185, 0
	s_cbranch_vccnz .LBB0_505
	global_load_dwordx4 v[132:135], v[128:129], off nt
	global_load_dwordx4 v[136:139], v[174:175], off offset:512 nt
	s_waitcnt vmcnt(1)
	v_pk_add_f32 v[134:135], v[134:135], 1.0 op_sel_hi:[1,0]
	v_pk_add_f32 v[132:133], v[132:133], 1.0 op_sel_hi:[1,0]
	s_waitcnt vmcnt(0)
	v_pk_mul_f32 v[184:185], v[138:139], v[134:135]
	v_pk_mul_f32 v[182:183], v[136:137], v[132:133]
.LBB0_505:
	global_load_dwordx4 v[156:159], v[130:131], off offset:16 nt
	s_and_b64 vcc, exec, s[8:9]
	v_mov_b32_e32 v181, 0
	v_mov_b32_e32 v186, 0
	v_mov_b32_e32 v187, 0
	s_cbranch_vccnz .LBB0_507
	global_load_dwordx4 v[128:131], v[128:129], off offset:16 nt
	s_nop 0
	global_load_dwordx4 v[132:135], v[174:175], off offset:528 nt
	s_waitcnt vmcnt(1)
	v_pk_add_f32 v[130:131], v[130:131], 1.0 op_sel_hi:[1,0]
	v_pk_add_f32 v[128:129], v[128:129], 1.0 op_sel_hi:[1,0]
	s_waitcnt vmcnt(0)
	v_pk_mul_f32 v[186:187], v[134:135], v[130:131]
	v_pk_mul_f32 v[180:181], v[132:133], v[128:129]
.LBB0_507:
	v_add_u32_e32 v176, v209, v207
	v_lshlrev_b64 v[214:215], 2, v[176:177]
	v_lshl_add_u64 v[128:129], s[34:35], 0, v[214:215]
	v_add_u32_e32 v198, 0x4000, v176
	v_mov_b32_e32 v199, v177
	global_load_dwordx4 v[210:213], v[128:129], off offset:16 nt
	global_load_dwordx4 v[232:235], v[128:129], off nt
	v_lshl_add_u64 v[128:129], v[198:199], 2, s[34:35]
	v_add_u32_e32 v196, 0x8000, v176
	v_mov_b32_e32 v197, v177
	v_add_u32_e32 v194, 0xc000, v176
	v_mov_b32_e32 v195, v177
	global_load_dwordx4 v[132:135], v[128:129], off offset:16 nt
	global_load_dwordx4 v[152:155], v[128:129], off nt
	v_lshl_add_u64 v[128:129], v[196:197], 2, s[34:35]
	v_lshl_add_u64 v[136:137], v[194:195], 2, s[34:35]
	global_load_dwordx4 v[144:147], v[128:129], off offset:16 nt
	global_load_dwordx4 v[148:151], v[128:129], off nt
	s_nop 0
	global_load_dwordx4 v[128:131], v[136:137], off offset:16 nt
	s_nop 0
	global_load_dwordx4 v[136:139], v[136:137], off nt
	s_mov_b32 s37, s36
	s_mov_b32 s38, s36
	s_mov_b32 s39, s36
	s_waitcnt vmcnt(8)
	v_pk_mul_f32 v[188:189], s[38:39], v[158:159]
	v_pk_mul_f32 v[174:175], s[36:37], v[156:157]
	v_pk_mul_f32 v[190:191], s[38:39], v[142:143]
	v_pk_mul_f32 v[192:193], s[36:37], v[140:141]
	s_and_b64 vcc, exec, s[8:9]
	v_lshl_add_u64 v[214:215], s[28:29], 0, v[214:215]
	s_waitcnt vmcnt(0)
	v_pk_fma_f32 v[142:143], v[114:115], v[188:189], v[212:213]
	s_waitcnt vmcnt(0)
	v_pk_fma_f32 v[158:159], v[118:119], v[190:191], v[234:235]
	v_pk_fma_f32 v[156:157], v[116:117], v[192:193], v[232:233]
	v_pk_fma_f32 v[140:141], v[112:113], v[174:175], v[210:211]
	global_store_dwordx4 v[214:215], v[156:159], off
	global_store_dwordx4 v[214:215], v[140:143], off offset:16
	s_cbranch_vccnz .LBB0_509
	v_pk_mul_f32 v[212:213], v[184:185], v[158:159]
	v_pk_mul_f32 v[210:211], v[182:183], v[156:157]
	v_pk_mul_f32 v[214:215], v[186:187], v[142:143]
	v_pk_mul_f32 v[232:233], v[180:181], v[140:141]
	v_cvt_pk_bf16_f32 v210, v210, v211
	v_cvt_pk_bf16_f32 v211, v212, v213
	s_nop 0
	v_cvt_pk_bf16_f32 v212, v232, v233
	v_cvt_pk_bf16_f32 v213, v214, v215
	v_lshl_add_u64 v[214:215], v[176:177], 1, s[26:27]
	global_store_dwordx4 v[214:215], v[210:213], off
	s_nop 1
	v_mov_b32_e32 v211, v140
	v_mov_b32_e32 v140, v157
	v_mov_b32_e32 v157, v142
	v_mov_b32_e32 v142, v159
	v_mov_b32_e32 v210, v156
	v_pk_mul_f32 v[140:141], v[140:141], v[140:141]
	v_mov_b32_e32 v156, v158
	v_pk_mul_f32 v[142:143], v[142:143], v[142:143]
	v_pk_fma_f32 v[140:141], v[210:211], v[210:211], v[140:141]
	v_pk_fma_f32 v[142:143], v[156:157], v[156:157], v[142:143]
	s_nop 0
	v_pk_add_f32 v[140:141], v[140:141], v[142:143]
	s_nop 0
	v_add_f32_e32 v140, v140, v141
	v_add_f32_e32 v173, v173, v140

; __device__ __forceinline__ unsigned cvt_pk_bf16(float lo, float hi) { unsigned r; asm volatile("v_cvt_pk_bf16_f32 %0, %1, %2" : "=v"(r) : "v"(lo), "v"(hi)); return r; }
; #define RES_LD(buf, pp) do { _Pragma("unroll") for (int j = 0; j < 2; ++j) { const int i_ = 2 * (pp) + j; const unsigned off_ = (row0 + (i_ >> 2) * HALF + (i_ & 3) * 16) * 1024u + col; \
;                 xq[buf][j][0] = *(const f32x4*)(xin + off_); xq[buf][j][1] = *(const f32x4*)(xin + off_ + 4); } } while (0)
;     static __device__ __forceinline__ void run(const f32x4 (&acc)[2][2][4][2], const Unit& u, int wr, int wc, int fr, int fq, const float* xin, float* xout, const float* gate, float gs, const float* lazy_ssq, const float* lazy_g, ...
;     ...
;             constexpr bool DEEP = !LAZY && !WG2;
;             if (DEEP) RES_LD(0, 0);
; #pragma unroll
;             for (int pp = 0; pp < 4; ++pp) {
;                 if (DEEP) { if (pp < 3) RES_LD((pp + 1) & 1, pp + 1); } else RES_LD(pp & 1, pp);
; #pragma unroll
;                 for (int j = 0; j < 2; ++j) { const int i_ = 2 * pp + j, ai = i_ >> 2, m = i_ & 3; const unsigned off = (row0 + ai * HALF + m * 16) * 1024u + col;
;                     const f32x4 xi0 = xq[pp & 1][j][0], xi1 = xq[pp & 1][j][1];
;                     f32x4 xo0 = gv[0] * acc[ai][bj][m][0], xo1 = gv[1] * acc[ai][bj][m][1];
;                     if (LAZY) { xo0 = xo0 + xi0 * lg[0] * rl[ai][m]; xo1 = xo1 + xi1 * lg[1] * rl[ai][m]; } else { xo0 = xo0 + xi0; xo1 = xo1 + xi1; }
;                     *(f32x4*)(xout + off) = xo0; *(f32x4*)(xout + off + 4) = xo1;
;                     if (aout) { const f32x4 a0 = xo0 * wv[0], a1 = xo1 * wv[1]; u32x4 w; w.x = cvt_pk_bf16(a0[0], a0[1]); w.y = cvt_pk_bf16(a0[2], a0[3]); w.z = cvt_pk_bf16(a1[0], a1[1]); w.w = cvt_pk_bf16(a1[2], a1[3]);
;                         *(u32x4*)(aout + off) = w;
;                         sq[ai][m] += ((xo0[0] * xo0[0] + xo0[1] * xo0[1]) + (xo0[2] * xo0[2] + xo0[3] * xo0[3])) + ((xo1[0] * xo1[0] + xo1[1] * xo1[1]) + (xo1[2] * xo1[2] + xo1[3] * xo1[3]));
.LBB0_511:
	v_add_u32_e32 v198, v208, v209
	v_mov_b32_e32 v199, v177
	v_lshl_add_u64 v[132:133], v[198:199], 2, s[34:35]
	global_load_dwordx4 v[152:155], v[132:133], off offset:16 nt
	global_load_dwordx4 v[156:159], v[132:133], off nt
	v_add_u32_e32 v132, 0x4000, v198
	v_mov_b32_e32 v133, v177
	v_lshl_add_u64 v[140:141], v[132:133], 2, s[34:35]
	global_load_dwordx4 v[132:135], v[140:141], off offset:16 nt
	s_nop 0
	global_load_dwordx4 v[140:143], v[140:141], off nt
	s_waitcnt vmcnt(0)
	v_pk_fma_f32 v[150:151], v[86:87], v[190:191], v[150:151]
	v_pk_fma_f32 v[148:149], v[84:85], v[192:193], v[148:149]
	v_pk_fma_f32 v[146:147], v[82:83], v[188:189], v[146:147]
	v_pk_fma_f32 v[144:145], v[80:81], v[174:175], v[144:145]
	v_lshl_add_u64 v[208:209], v[196:197], 2, s[28:29]
	s_and_b64 vcc, exec, s[8:9]
	global_store_dwordx4 v[208:209], v[148:151], off
	global_store_dwordx4 v[208:209], v[144:147], off offset:16
	s_cbranch_vccnz .LBB0_513
	v_pk_mul_f32 v[210:211], v[184:185], v[150:151]
	v_pk_mul_f32 v[208:209], v[182:183], v[148:149]
	v_lshl_add_u64 v[196:197], v[196:197], 1, s[26:27]
	v_pk_mul_f32 v[212:213], v[186:187], v[146:147]
	v_pk_mul_f32 v[214:215], v[180:181], v[144:145]
	v_cvt_pk_bf16_f32 v208, v208, v209
	v_cvt_pk_bf16_f32 v209, v210, v211
	s_nop 0
	v_cvt_pk_bf16_f32 v210, v214, v215
	v_cvt_pk_bf16_f32 v211, v212, v213
	global_store_dwordx4 v[196:197], v[208:211], off
	v_mov_b32_e32 v197, v144
	v_mov_b32_e32 v144, v149
	v_mov_b32_e32 v149, v146
	v_mov_b32_e32 v146, v151
	v_mov_b32_e32 v196, v148
	v_pk_mul_f32 v[144:145], v[144:145], v[144:145]
	v_mov_b32_e32 v148, v150
	v_pk_mul_f32 v[146:147], v[146:147], v[146:147]
	v_pk_fma_f32 v[144:145], v[196:197], v[196:197], v[144:145]
	v_pk_fma_f32 v[146:147], v[148:149], v[148:149], v[146:147]
	s_nop 0
	v_pk_add_f32 v[144:145], v[144:145], v[146:147]
	s_nop 0
	v_add_f32_e32 v144, v144, v145
	v_add_f32_e32 v205, v205, v144

; __device__ __forceinline__ unsigned cvt_pk_bf16(float lo, float hi) { unsigned r; asm volatile("v_cvt_pk_bf16_f32 %0, %1, %2" : "=v"(r) : "v"(lo), "v"(hi)); return r; }
; #define RES_LD(buf, pp) do { _Pragma("unroll") for (int j = 0; j < 2; ++j) { const int i_ = 2 * (pp) + j; const unsigned off_ = (row0 + (i_ >> 2) * HALF + (i_ & 3) * 16) * 1024u + col; \
;                 xq[buf][j][0] = *(const f32x4*)(xin + off_); xq[buf][j][1] = *(const f32x4*)(xin + off_ + 4); } } while (0)
;     static __device__ __forceinline__ void run(const f32x4 (&acc)[2][2][4][2], const Unit& u, int wr, int wc, int fr, int fq, const float* xin, float* xout, const float* gate, float gs, const float* lazy_ssq, const float* lazy_g, ...
;     ...
;             constexpr bool DEEP = !LAZY && !WG2;
;             if (DEEP) RES_LD(0, 0);
; #pragma unroll
;             for (int pp = 0; pp < 4; ++pp) {
;                 if (DEEP) { if (pp < 3) RES_LD((pp + 1) & 1, pp + 1); } else RES_LD(pp & 1, pp);
; #pragma unroll
;                 for (int j = 0; j < 2; ++j) { const int i_ = 2 * pp + j, ai = i_ >> 2, m = i_ & 3; const unsigned off = (row0 + ai * HALF + m * 16) * 1024u + col;
;                     const f32x4 xi0 = xq[pp & 1][j][0], xi1 = xq[pp & 1][j][1];
;                     f32x4 xo0 = gv[0] * acc[ai][bj][m][0], xo1 = gv[1] * acc[ai][bj][m][1];
;                     if (LAZY) { xo0 = xo0 + xi0 * lg[0] * rl[ai][m]; xo1 = xo1 + xi1 * lg[1] * rl[ai][m]; } else { xo0 = xo0 + xi0; xo1 = xo1 + xi1; }
;                     *(f32x4*)(xout + off) = xo0; *(f32x4*)(xout + off + 4) = xo1;
;                     if (aout) { const f32x4 a0 = xo0 * wv[0], a1 = xo1 * wv[1]; u32x4 w; w.x = cvt_pk_bf16(a0[0], a0[1]); w.y = cvt_pk_bf16(a0[2], a0[3]); w.z = cvt_pk_bf16(a1[0], a1[1]); w.w = cvt_pk_bf16(a1[2], a1[3]);
;                         *(u32x4*)(aout + off) = w;
;                         sq[ai][m] += ((xo0[0] * xo0[0] + xo0[1] * xo0[1]) + (xo0[2] * xo0[2] + xo0[3] * xo0[3])) + ((xo1[0] * xo1[0] + xo1[1] * xo1[1]) + (xo1[2] * xo1[2] + xo1[3] * xo1[3]));
.LBB0_515:
	s_nop 0
	v_add_u32_e32 v128, 0x8000, v198
	v_mov_b32_e32 v129, v177
	v_lshl_add_u64 v[128:129], v[128:129], 2, s[34:35]
	global_load_dwordx4 v[144:147], v[128:129], off offset:16 nt
	global_load_dwordx4 v[148:151], v[128:129], off nt
	v_add_u32_e32 v128, 0xc000, v198
	v_mov_b32_e32 v129, v177
	v_lshl_add_u64 v[136:137], v[128:129], 2, s[34:35]
	global_load_dwordx4 v[128:131], v[136:137], off offset:16 nt
	s_nop 0
	global_load_dwordx4 v[136:139], v[136:137], off nt
	v_add_u32_e32 v194, 0x20000, v176
	v_mov_b32_e32 v195, v177
	s_waitcnt vmcnt(0)
	v_pk_fma_f32 v[158:159], v[54:55], v[190:191], v[158:159]
	v_pk_fma_f32 v[156:157], v[52:53], v[192:193], v[156:157]
	v_pk_fma_f32 v[154:155], v[50:51], v[188:189], v[154:155]
	v_pk_fma_f32 v[152:153], v[48:49], v[174:175], v[152:153]
	v_lshl_add_u64 v[196:197], v[194:195], 2, s[28:29]
	s_and_b64 vcc, exec, s[8:9]
	global_store_dwordx4 v[196:197], v[156:159], off
	global_store_dwordx4 v[196:197], v[152:155], off offset:16
	s_cbranch_vccnz .LBB0_517
	v_pk_mul_f32 v[198:199], v[184:185], v[158:159]
	v_pk_mul_f32 v[196:197], v[182:183], v[156:157]
	v_lshl_add_u64 v[194:195], v[194:195], 1, s[26:27]
	v_pk_mul_f32 v[208:209], v[186:187], v[154:155]
	v_pk_mul_f32 v[210:211], v[180:181], v[152:153]
	v_cvt_pk_bf16_f32 v196, v196, v197
	v_cvt_pk_bf16_f32 v197, v198, v199
	s_nop 0
	v_cvt_pk_bf16_f32 v198, v210, v211
	v_cvt_pk_bf16_f32 v199, v208, v209
	global_store_dwordx4 v[194:195], v[196:199], off
	v_mov_b32_e32 v195, v152
	v_mov_b32_e32 v152, v157
	v_mov_b32_e32 v157, v154
	v_mov_b32_e32 v154, v159
	v_mov_b32_e32 v194, v156
	v_pk_mul_f32 v[152:153], v[152:153], v[152:153]
	v_mov_b32_e32 v156, v158
	v_pk_mul_f32 v[154:155], v[154:155], v[154:155]
	v_pk_fma_f32 v[152:153], v[194:195], v[194:195], v[152:153]
	v_pk_fma_f32 v[154:155], v[156:157], v[156:157], v[154:155]
	s_nop 0
	v_pk_add_f32 v[152:153], v[152:153], v[154:155]
	s_nop 0
	v_add_f32_e32 v152, v152, v153
	v_add_f32_e32 v201, v201, v152
